# ret far-key Q load ladder de-serialised; conv layernorm parameter loads issued at unit head
# baseline (speedup 1.0000x reference)
.LBB0_870:
	v_lshlrev_b32_e32 v32, 5, v194
	v_or_b32_e32 v66, v32, v191
	v_readlane_b32 s14, v254, 11
	v_ashrrev_i32_e32 v67, 31, v66
	v_readlane_b32 s15, v254, 12
	v_lshl_add_u64 v[34:35], s[12:13], 0, v[66:67]
	v_lshlrev_b32_e32 v152, 3, v195
	v_mov_b64_e32 v[36:37], s[14:15]
	v_mad_u64_u32 v[36:37], s[0:1], v34, s60, v[36:37]
	v_mad_i32_i24 v37, v35, s60, v37
	v_lshl_add_u64 v[58:59], v[36:37], 0, v[152:153]
	global_load_dwordx2 v[34:35], v[58:59], off
	global_load_dwordx2 v[42:43], v[58:59], off offset:64
	global_load_dwordx2 v[104:105], v[58:59], off offset:16
	global_load_dwordx2 v[106:107], v[58:59], off offset:80
	global_load_dwordx2 v[108:109], v[58:59], off offset:32
	global_load_dwordx2 v[110:111], v[58:59], off offset:96
	global_load_dwordx2 v[112:113], v[58:59], off offset:48
	global_load_dwordx2 v[114:115], v[58:59], off offset:112
	v_cvt_f32_i32_e32 v65, v66
	v_sub_u32_e32 v66, 0xff, v66
	v_cvt_f32_i32_e32 v66, v66
	v_mul_f32_e32 v65, v193, v65
	v_exp_f32_e32 v65, v65
	v_mul_f32_e32 v66, v192, v66
	v_exp_f32_e32 v102, v66
	s_waitcnt vmcnt(7)
	v_lshlrev_b32_e32 v38, 16, v34
	v_and_b32_e32 v37, 0xffff0000, v34
	s_waitcnt vmcnt(6)
	v_lshlrev_b32_e32 v46, 16, v42
	v_and_b32_e32 v44, 0xffff0000, v42
	v_lshlrev_b32_e32 v41, 16, v43
	v_and_b32_e32 v34, 0xffff0000, v43
	v_lshlrev_b32_e32 v36, 16, v35
	v_and_b32_e32 v33, 0xffff0000, v35
	v_mul_f32_e32 v67, v65, v38
	v_mul_f32_e32 v74, v65, v46
	v_mul_f32_e32 v75, v65, v44
	v_mul_f32_e32 v76, v65, v41
	v_mul_f32_e32 v70, v65, v33
	v_mul_f32_e32 v77, v65, v34
	s_waitcnt vmcnt(5)
	v_lshlrev_b32_e32 v39, 16, v105
	v_and_b32_e32 v35, 0xffff0000, v105
	s_waitcnt vmcnt(4)
	v_lshlrev_b32_e32 v48, 16, v106
	v_and_b32_e32 v47, 0xffff0000, v106
	v_lshlrev_b32_e32 v43, 16, v107
	v_and_b32_e32 v40, 0xffff0000, v107
	v_lshlrev_b32_e32 v45, 16, v104
	v_and_b32_e32 v42, 0xffff0000, v104
	v_mul_f32_e32 v71, v65, v45
	v_mul_f32_e32 v78, v65, v48
	v_mul_f32_e32 v72, v65, v42
	v_mul_f32_e32 v79, v65, v47
	v_mul_f32_e32 v73, v65, v39
	v_mul_f32_e32 v80, v65, v43
	v_mul_f32_e32 v81, v65, v35
	v_mul_f32_e32 v82, v65, v40
	s_waitcnt vmcnt(3)
	v_lshlrev_b32_e32 v54, 16, v108
	v_and_b32_e32 v52, 0xffff0000, v108
	v_lshlrev_b32_e32 v50, 16, v109
	v_and_b32_e32 v49, 0xffff0000, v109
	s_waitcnt vmcnt(2)
	v_lshlrev_b32_e32 v56, 16, v110
	v_and_b32_e32 v55, 0xffff0000, v110
	v_lshlrev_b32_e32 v53, 16, v111
	v_and_b32_e32 v51, 0xffff0000, v111
	v_mul_f32_e32 v83, v65, v54
	v_mul_f32_e32 v84, v65, v56
	v_mul_f32_e32 v85, v65, v52
	v_mul_f32_e32 v86, v65, v55
	v_mul_f32_e32 v87, v65, v50
	v_mul_f32_e32 v88, v65, v53
	v_mul_f32_e32 v89, v65, v49
	v_mul_f32_e32 v90, v65, v51
	s_waitcnt vmcnt(1)
	v_lshlrev_b32_e32 v62, 16, v112
	v_and_b32_e32 v60, 0xffff0000, v112
	v_lshlrev_b32_e32 v58, 16, v113
	v_and_b32_e32 v57, 0xffff0000, v113
	s_waitcnt vmcnt(0)
	v_lshlrev_b32_e32 v64, 16, v114
	v_and_b32_e32 v63, 0xffff0000, v114
	v_lshlrev_b32_e32 v61, 16, v115
	v_and_b32_e32 v59, 0xffff0000, v115
	v_mul_f32_e32 v68, v65, v37
	v_mul_f32_e32 v69, v65, v36
	v_mul_f32_e32 v91, v65, v62
	v_mul_f32_e32 v92, v65, v64
	v_mul_f32_e32 v93, v65, v60
	v_mul_f32_e32 v94, v65, v63
	v_mul_f32_e32 v95, v65, v58
	v_mul_f32_e32 v96, v65, v61
	v_mul_f32_e32 v97, v65, v57
	v_mul_f32_e32 v65, v65, v59
	v_cvt_pk_bf16_f32 v66, v67, v68
	v_cvt_pk_bf16_f32 v67, v69, v70
	v_cvt_pk_bf16_f32 v68, v71, v72
	v_cvt_pk_bf16_f32 v69, v73, v81
	v_cvt_pk_bf16_f32 v70, v83, v85
	v_cvt_pk_bf16_f32 v71, v87, v89
	v_cvt_pk_bf16_f32 v72, v91, v93
	v_cvt_pk_bf16_f32 v73, v95, v97
	v_cvt_pk_bf16_f32 v74, v74, v75
	v_cvt_pk_bf16_f32 v75, v76, v77
	v_cvt_pk_bf16_f32 v76, v78, v79
	v_cvt_pk_bf16_f32 v77, v80, v82
	v_cvt_pk_bf16_f32 v78, v84, v86
	v_cvt_pk_bf16_f32 v79, v88, v90
	v_cvt_pk_bf16_f32 v80, v92, v94
	v_cvt_pk_bf16_f32 v81, v96, v65
	s_nop 0
	v_permlane32_swap_b32_e32 v66, v68
	v_permlane32_swap_b32_e32 v67, v69
	v_permlane32_swap_b32_e32 v70, v72
	v_permlane32_swap_b32_e32 v71, v73
	v_permlane32_swap_b32_e32 v74, v76
	v_permlane32_swap_b32_e32 v75, v77
	v_permlane32_swap_b32_e32 v78, v80
	v_permlane32_swap_b32_e32 v79, v81
	s_cmp_lg_u32 0, -1
	s_cselect_b32 s0, 0, 0
	s_add_i32 s1, s0, 0x18000
	v_add_u32_e32 v65, s1, v171
	ds_read_b64_tr_b16 v[82:83], v65 offset:0
	ds_read_b64_tr_b16 v[84:85], v65 offset:0x400
	ds_read_b64_tr_b16 v[86:87], v65 offset:0x800
	ds_read_b64_tr_b16 v[88:89], v65 offset:0xc00
	ds_read_b64_tr_b16 v[90:91], v65 offset:0x1000
	ds_read_b64_tr_b16 v[92:93], v65 offset:0x1400
	ds_read_b64_tr_b16 v[94:95], v65 offset:0x1800
	ds_read_b64_tr_b16 v[96:97], v65 offset:0x1c00
	s_waitcnt lgkmcnt(0)
	s_nop 0
	v_mfma_f32_32x32x16_bf16 v[0:15], v[66:69], v[82:85], v[0:15]
	ds_read_b64_tr_b16 v[82:83], v65 offset:0x200
	ds_read_b64_tr_b16 v[84:85], v65 offset:0x600
	v_mfma_f32_32x32x16_bf16 v[0:15], v[70:73], v[86:89], v[0:15]
	ds_read_b64_tr_b16 v[86:87], v65 offset:0xa00
	ds_read_b64_tr_b16 v[88:89], v65 offset:0xe00
	v_mfma_f32_32x32x16_bf16 v[0:15], v[74:77], v[90:93], v[0:15]
	ds_read_b64_tr_b16 v[90:91], v65 offset:0x1200
	ds_read_b64_tr_b16 v[92:93], v65 offset:0x1600
	ds_read_b64_tr_b16 v[98:99], v65 offset:0x1a00
	ds_read_b64_tr_b16 v[100:101], v65 offset:0x1e00
	s_waitcnt lgkmcnt(0)
	v_mfma_f32_32x32x16_bf16 v[16:31], v[66:69], v[82:85], v[16:31]
	v_mul_f32_e32 v38, v102, v38
	v_mul_f32_e32 v46, v102, v46
	v_mul_f32_e32 v37, v102, v37
	v_mul_f32_e32 v44, v102, v44
	v_mul_f32_e32 v36, v102, v36
	v_mul_f32_e32 v65, v102, v41
	v_mul_f32_e32 v41, v102, v45
	v_mfma_f32_32x32x16_bf16 v[16:31], v[70:73], v[86:89], v[16:31]
	v_mul_f32_e32 v45, v102, v48
	v_mul_f32_e32 v42, v102, v42
	v_mul_f32_e32 v47, v102, v47
	v_mul_f32_e32 v39, v102, v39
	v_mul_f32_e32 v48, v102, v43
	v_mul_f32_e32 v43, v102, v35
	v_mul_f32_e32 v66, v102, v40
	v_mfma_f32_32x32x16_bf16 v[16:31], v[74:77], v[90:93], v[16:31]
	v_mul_f32_e32 v40, v102, v54
	v_mul_f32_e32 v49, v102, v49
	v_mul_f32_e32 v33, v102, v33
	v_mul_f32_e32 v54, v102, v56
	v_mul_f32_e32 v52, v102, v52
	v_mul_f32_e32 v55, v102, v55
	v_mul_f32_e32 v50, v102, v50
	v_mfma_f32_32x32x16_bf16 v[0:15], v[78:81], v[94:97], v[0:15]
	v_mul_f32_e32 v94, v102, v34
	v_mul_f32_e32 v53, v102, v53
	v_mul_f32_e32 v51, v102, v51
	v_mul_f32_e32 v56, v102, v62
	v_mul_f32_e32 v62, v102, v64
	v_mul_f32_e32 v60, v102, v60
	v_mul_f32_e32 v63, v102, v63
	v_mul_f32_e32 v58, v102, v58
	v_mul_f32_e32 v61, v102, v61
	v_mul_f32_e32 v57, v102, v57
	v_mul_f32_e32 v59, v102, v59
	v_cvt_pk_bf16_f32 v34, v38, v37
	v_cvt_pk_bf16_f32 v35, v36, v33
	v_cvt_pk_bf16_f32 v36, v41, v42
	v_cvt_pk_bf16_f32 v37, v39, v43
	v_cvt_pk_bf16_f32 v38, v40, v52
	v_cvt_pk_bf16_f32 v39, v50, v49
	v_cvt_pk_bf16_f32 v40, v56, v60
	v_cvt_pk_bf16_f32 v41, v58, v57
	v_cvt_pk_bf16_f32 v42, v46, v44
	v_cvt_pk_bf16_f32 v43, v65, v94
	v_cvt_pk_bf16_f32 v44, v45, v47
	v_cvt_pk_bf16_f32 v45, v48, v66
	v_cvt_pk_bf16_f32 v46, v54, v55
	v_cvt_pk_bf16_f32 v47, v53, v51
	v_cvt_pk_bf16_f32 v48, v62, v63
	v_cvt_pk_bf16_f32 v49, v61, v59
	v_mfma_f32_32x32x16_bf16 v[16:31], v[78:81], v[98:101], v[16:31]
	v_permlane32_swap_b32_e32 v34, v36
	v_permlane32_swap_b32_e32 v35, v37
	v_permlane32_swap_b32_e32 v38, v40
	v_permlane32_swap_b32_e32 v39, v41
	v_permlane32_swap_b32_e32 v42, v44
	v_permlane32_swap_b32_e32 v43, v45
	v_permlane32_swap_b32_e32 v46, v48
	v_permlane32_swap_b32_e32 v47, v49
	s_add_i32 s0, s0, 0x1a000
	v_add_u32_e32 v33, s0, v171
	ds_read_b64_tr_b16 v[50:51], v33 offset:0
	ds_read_b64_tr_b16 v[52:53], v33 offset:0x400
	ds_read_b64_tr_b16 v[54:55], v33 offset:0x800
	ds_read_b64_tr_b16 v[56:57], v33 offset:0xc00
	ds_read_b64_tr_b16 v[58:59], v33 offset:0x1000
	ds_read_b64_tr_b16 v[60:61], v33 offset:0x1400
	ds_read_b64_tr_b16 v[62:63], v33 offset:0x1800
	ds_read_b64_tr_b16 v[64:65], v33 offset:0x1c00
	s_waitcnt lgkmcnt(0)
	s_nop 0
	v_mfma_f32_32x32x16_bf16 v[0:15], v[34:37], v[50:53], v[0:15]
	ds_read_b64_tr_b16 v[50:51], v33 offset:0x200
	ds_read_b64_tr_b16 v[52:53], v33 offset:0x600
	v_mfma_f32_32x32x16_bf16 v[0:15], v[38:41], v[54:57], v[0:15]
	v_mfma_f32_32x32x16_bf16 v[0:15], v[42:45], v[58:61], v[0:15]
	ds_read_b64_tr_b16 v[58:59], v33 offset:0xa00
	ds_read_b64_tr_b16 v[60:61], v33 offset:0xe00
	ds_read_b64_tr_b16 v[66:67], v33 offset:0x1200
	ds_read_b64_tr_b16 v[68:69], v33 offset:0x1600
	ds_read_b64_tr_b16 v[70:71], v33 offset:0x1a00
	ds_read_b64_tr_b16 v[72:73], v33 offset:0x1e00
	s_waitcnt lgkmcnt(0)
	v_mfma_f32_32x32x16_bf16 v[0:15], v[46:49], v[62:65], v[0:15]
	v_mfma_f32_32x32x16_bf16 v[16:31], v[34:37], v[50:53], v[16:31]
	v_ashrrev_i32_e32 v33, 31, v32
	v_lshl_add_u64 v[62:63], s[12:13], 0, v[32:33]
	v_mov_b32_e32 v121, v153
	v_lshl_or_b32 v62, v195, 2, v62
	v_lshl_add_u64 v[90:91], s[14:15], 0, v[120:121]
	v_or_b32_e32 v56, 1, v62
	v_or_b32_e32 v54, 2, v62
	v_mfma_f32_32x32x16_bf16 v[16:31], v[38:41], v[58:61], v[16:31]
	v_or_b32_e32 v52, 3, v62
	v_or_b32_e32 v50, 8, v62
	v_or_b32_e32 v40, 17, v62
	v_or_b32_e32 v38, 18, v62
	v_or_b32_e32 v36, 19, v62
	v_or_b32_e32 v34, 24, v62
	v_or_b32_e32 v32, 25, v62
	v_mfma_f32_32x32x16_bf16 v[16:31], v[42:45], v[66:69], v[16:31]
	v_or_b32_e32 v44, 11, v62
	v_or_b32_e32 v42, 16, v62
	v_or_b32_e32 v58, 26, v62
	v_mad_u64_u32 v[92:93], s[0:1], v62, s60, v[90:91]
	v_mad_u64_u32 v[94:95], s[0:1], v56, s60, v[90:91]
	v_mfma_f32_32x32x16_bf16 v[16:31], v[46:49], v[70:73], v[16:31]
	v_or_b32_e32 v48, 9, v62
	v_or_b32_e32 v46, 10, v62
	v_mad_u64_u32 v[64:65], s[0:1], v54, s60, v[90:91]
	v_mad_u64_u32 v[66:67], s[0:1], v52, s60, v[90:91]
	v_mad_u64_u32 v[68:69], s[0:1], v50, s60, v[90:91]
	s_nop 6
	v_add_f32_e32 v88, v1, v17
	v_add_f32_e32 v60, v0, v16
	ds_bpermute_b32 v89, v202, v88
	ds_bpermute_b32 v61, v202, v60
	v_add_f32_e32 v100, v2, v18
	v_add_f32_e32 v102, v3, v19
	ds_bpermute_b32 v101, v202, v100
	s_waitcnt lgkmcnt(2)
	v_add_f32_e32 v96, v88, v89
	s_waitcnt lgkmcnt(1)
	v_add_f32_e32 v60, v60, v61
	ds_bpermute_b32 v97, v203, v96
	ds_bpermute_b32 v61, v203, v60
	ds_bpermute_b32 v103, v202, v102
	v_add_f32_e32 v104, v5, v21
	ds_bpermute_b32 v105, v202, v104
	s_waitcnt lgkmcnt(3)
	v_add_f32_e32 v96, v96, v97
	s_waitcnt lgkmcnt(2)
	v_add_f32_e32 v98, v60, v61
	ds_bpermute_b32 v97, v204, v96
	ds_bpermute_b32 v99, v204, v98
	v_add_f32_e32 v106, v7, v23
	ds_bpermute_b32 v107, v202, v106
	v_add_f32_e32 v108, v9, v25
	s_waitcnt lgkmcnt(2)
	v_add_f32_e32 v96, v96, v97
	s_waitcnt lgkmcnt(1)
	v_add_f32_e32 v98, v98, v99
	ds_bpermute_b32 v97, v205, v96
	ds_bpermute_b32 v99, v205, v98
	s_waitcnt lgkmcnt(2)
	v_add_f32_e32 v106, v106, v107
	ds_bpermute_b32 v107, v203, v106
	ds_bpermute_b32 v109, v202, v108
	s_waitcnt lgkmcnt(3)
	v_add_f32_e32 v96, v96, v97
	s_waitcnt lgkmcnt(2)
	v_add_f32_e32 v98, v98, v99
	ds_bpermute_b32 v97, v206, v96
	ds_bpermute_b32 v99, v206, v98
	s_waitcnt lgkmcnt(3)
	v_add_f32_e32 v106, v106, v107
	ds_bpermute_b32 v107, v204, v106
	v_add_f32_e32 v110, v11, v27
	s_waitcnt lgkmcnt(2)
	v_add_f32_e32 v97, v96, v97
	v_add_f32_e32 v96, v100, v101
	v_add_f32_e32 v100, v102, v103
	v_add_f32_e32 v102, v4, v20
	s_waitcnt lgkmcnt(1)
	v_add_f32_e32 v98, v98, v99
	ds_bpermute_b32 v99, v203, v96
	ds_bpermute_b32 v103, v202, v102
	ds_bpermute_b32 v101, v203, v100
	s_waitcnt lgkmcnt(3)
	v_add_f32_e32 v106, v106, v107
	ds_bpermute_b32 v107, v205, v106
	s_waitcnt lgkmcnt(3)
	v_add_f32_e32 v96, v96, v99
	s_waitcnt lgkmcnt(2)
	v_add_f32_e32 v102, v102, v103
	ds_bpermute_b32 v99, v204, v96
	ds_bpermute_b32 v103, v203, v102
	s_waitcnt lgkmcnt(3)
	v_add_f32_e32 v100, v100, v101
	ds_bpermute_b32 v101, v204, v100
	ds_bpermute_b32 v111, v202, v110
	s_waitcnt lgkmcnt(3)
	v_add_f32_e32 v96, v96, v99
	s_waitcnt lgkmcnt(2)
	v_add_f32_e32 v102, v102, v103
	ds_bpermute_b32 v99, v205, v96
	ds_bpermute_b32 v103, v204, v102
	s_waitcnt lgkmcnt(3)
	v_add_f32_e32 v100, v100, v101
	ds_bpermute_b32 v101, v205, v100
	v_add_f32_e32 v112, v13, v29
	s_waitcnt lgkmcnt(2)
	v_add_f32_e32 v96, v96, v99
	s_waitcnt lgkmcnt(1)
	v_add_f32_e32 v102, v102, v103
	ds_bpermute_b32 v99, v206, v96
	ds_bpermute_b32 v103, v205, v102
	s_waitcnt lgkmcnt(2)
	v_add_f32_e32 v100, v100, v101
	ds_bpermute_b32 v101, v206, v100
	ds_bpermute_b32 v113, v202, v112
	s_waitcnt lgkmcnt(3)
	v_add_f32_e32 v99, v96, v99
	s_waitcnt lgkmcnt(2)
	v_add_f32_e32 v96, v102, v103
	v_add_f32_e32 v102, v104, v105
	v_add_f32_e32 v104, v6, v22
	ds_bpermute_b32 v105, v202, v104
	ds_bpermute_b32 v103, v203, v102
	s_waitcnt lgkmcnt(3)
	v_add_f32_e32 v100, v100, v101
	ds_bpermute_b32 v101, v206, v96
	s_waitcnt lgkmcnt(3)
	v_add_f32_e32 v112, v112, v113
	s_waitcnt lgkmcnt(2)
	v_add_f32_e32 v104, v104, v105
	s_waitcnt lgkmcnt(1)
	v_add_f32_e32 v102, v102, v103
	ds_bpermute_b32 v105, v203, v104
	ds_bpermute_b32 v103, v204, v102
	s_waitcnt lgkmcnt(2)
	v_add_f32_e32 v101, v96, v101
	ds_bpermute_b32 v113, v203, v112
	v_add_f32_e32 v114, v14, v30
	s_waitcnt lgkmcnt(2)
	v_add_f32_e32 v104, v104, v105
	s_waitcnt lgkmcnt(1)
	v_add_f32_e32 v102, v102, v103
	ds_bpermute_b32 v105, v204, v104
	ds_bpermute_b32 v103, v205, v102
	s_waitcnt lgkmcnt(2)
	v_add_f32_e32 v112, v112, v113
	ds_bpermute_b32 v113, v204, v112
	ds_bpermute_b32 v115, v202, v114
	s_waitcnt lgkmcnt(3)
	v_add_f32_e32 v104, v104, v105
	s_waitcnt lgkmcnt(2)
	v_add_f32_e32 v102, v102, v103
	ds_bpermute_b32 v105, v205, v104
	ds_bpermute_b32 v103, v206, v102
	s_waitcnt lgkmcnt(3)
	v_add_f32_e32 v112, v112, v113
	ds_bpermute_b32 v113, v205, v112
	s_waitcnt lgkmcnt(3)
	v_add_f32_e32 v114, v114, v115
	s_waitcnt lgkmcnt(2)
	v_add_f32_e32 v96, v104, v105
	v_add_f32_e32 v104, v106, v107
	v_add_f32_e32 v106, v8, v24
	s_waitcnt lgkmcnt(1)
	v_add_f32_e32 v102, v102, v103
	ds_bpermute_b32 v103, v206, v96
	ds_bpermute_b32 v107, v202, v106
	ds_bpermute_b32 v105, v206, v104
	ds_bpermute_b32 v115, v203, v114
	s_waitcnt lgkmcnt(4)
	v_add_f32_e32 v112, v112, v113
	s_waitcnt lgkmcnt(3)
	v_add_f32_e32 v103, v96, v103
	s_waitcnt lgkmcnt(2)
	v_add_f32_e32 v96, v106, v107
	v_add_f32_e32 v106, v108, v109
	v_add_f32_e32 v108, v10, v26
	s_waitcnt lgkmcnt(1)
	v_add_f32_e32 v104, v104, v105
	ds_bpermute_b32 v105, v203, v96
	ds_bpermute_b32 v109, v202, v108
	ds_bpermute_b32 v107, v203, v106
	ds_bpermute_b32 v113, v206, v112
	v_fmamk_f32 v16, v98, 0xbc800000, v16
	s_waitcnt lgkmcnt(3)
	v_add_f32_e32 v96, v96, v105
	s_waitcnt lgkmcnt(2)
	v_add_f32_e32 v108, v108, v109
	ds_bpermute_b32 v105, v204, v96
	ds_bpermute_b32 v109, v203, v108
	s_waitcnt lgkmcnt(3)
	v_add_f32_e32 v106, v106, v107
	ds_bpermute_b32 v107, v204, v106
	v_fmamk_f32 v17, v97, 0xbc800000, v17
	s_waitcnt lgkmcnt(2)
	v_add_f32_e32 v96, v96, v105
	s_waitcnt lgkmcnt(1)
	v_add_f32_e32 v108, v108, v109
	ds_bpermute_b32 v105, v205, v96
	ds_bpermute_b32 v109, v204, v108
	s_waitcnt lgkmcnt(2)
	v_add_f32_e32 v106, v106, v107
	ds_bpermute_b32 v107, v205, v106
	v_or_b32_e32 v60, 27, v62
	s_waitcnt lgkmcnt(2)
	v_add_f32_e32 v96, v96, v105
	s_waitcnt lgkmcnt(1)
	v_add_f32_e32 v108, v108, v109
	ds_bpermute_b32 v105, v206, v96
	ds_bpermute_b32 v109, v205, v108
	s_waitcnt lgkmcnt(2)
	v_add_f32_e32 v106, v106, v107
	ds_bpermute_b32 v107, v206, v106
	v_mad_u64_u32 v[70:71], s[0:1], v48, s60, v[90:91]
	s_waitcnt lgkmcnt(2)
	v_add_f32_e32 v105, v96, v105
	s_waitcnt lgkmcnt(1)
	v_add_f32_e32 v96, v108, v109
	v_add_f32_e32 v108, v110, v111
	v_add_f32_e32 v110, v12, v28
	ds_bpermute_b32 v111, v202, v110
	ds_bpermute_b32 v109, v203, v108
	s_waitcnt lgkmcnt(2)
	v_add_f32_e32 v106, v106, v107
	ds_bpermute_b32 v107, v206, v96
	v_mad_u64_u32 v[72:73], s[0:1], v46, s60, v[90:91]
	s_waitcnt lgkmcnt(2)
	v_add_f32_e32 v110, v110, v111
	ds_bpermute_b32 v111, v203, v110
	s_waitcnt lgkmcnt(2)
	v_add_f32_e32 v108, v108, v109
	ds_bpermute_b32 v109, v204, v108
	s_waitcnt lgkmcnt(2)
	v_add_f32_e32 v107, v96, v107
	v_add_f32_e32 v96, v114, v115
	s_waitcnt lgkmcnt(1)
	v_add_f32_e32 v110, v110, v111
	ds_bpermute_b32 v111, v204, v110
	s_waitcnt lgkmcnt(1)
	v_add_f32_e32 v108, v108, v109
	ds_bpermute_b32 v109, v205, v108
	v_fmamk_f32 v114, v98, 0xbc800000, v0
	v_mul_f32_e32 v0, v16, v16
	s_waitcnt lgkmcnt(1)
	v_add_f32_e32 v110, v110, v111
	ds_bpermute_b32 v111, v205, v110
	s_waitcnt lgkmcnt(1)
	v_add_f32_e32 v108, v108, v109
	ds_bpermute_b32 v109, v206, v108
	v_fmac_f32_e32 v0, v114, v114
	ds_bpermute_b32 v98, v202, v0
	s_waitcnt lgkmcnt(2)
	v_add_f32_e32 v110, v110, v111
	ds_bpermute_b32 v111, v206, v110
	s_waitcnt lgkmcnt(2)
	v_add_f32_e32 v108, v108, v109
	v_mad_u64_u32 v[74:75], s[0:1], v44, s60, v[90:91]
	s_waitcnt lgkmcnt(1)
	v_add_f32_e32 v0, v0, v98
	s_waitcnt lgkmcnt(0)
	v_add_f32_e32 v109, v110, v111
	ds_bpermute_b32 v111, v204, v96
	v_add_f32_e32 v110, v112, v113
	v_add_f32_e32 v112, v15, v31
	ds_bpermute_b32 v113, v202, v112
	ds_bpermute_b32 v98, v203, v0
	s_waitcnt lgkmcnt(2)
	v_add_f32_e32 v96, v96, v111
	ds_bpermute_b32 v111, v205, v96
	v_mad_u64_u32 v[76:77], s[0:1], v42, s60, v[90:91]
	s_waitcnt lgkmcnt(2)
	v_add_f32_e32 v112, v112, v113
	ds_bpermute_b32 v113, v203, v112
	s_waitcnt lgkmcnt(1)
	v_add_f32_e32 v111, v96, v111
	v_fmamk_f32 v96, v97, 0xbc800000, v1
	v_mul_f32_e32 v1, v17, v17
	v_fmac_f32_e32 v1, v96, v96
	ds_bpermute_b32 v97, v202, v1
	v_add_f32_e32 v0, v0, v98
	s_waitcnt lgkmcnt(1)
	v_add_f32_e32 v112, v112, v113
	ds_bpermute_b32 v98, v204, v0
	ds_bpermute_b32 v113, v204, v112
	s_waitcnt lgkmcnt(2)
	v_add_f32_e32 v1, v1, v97
	ds_bpermute_b32 v97, v203, v1
	ds_bpermute_b32 v115, v206, v111
	s_waitcnt lgkmcnt(3)
	v_add_f32_e32 v0, v0, v98
	s_waitcnt lgkmcnt(2)
	v_add_f32_e32 v112, v112, v113
	ds_bpermute_b32 v98, v205, v0
	ds_bpermute_b32 v113, v205, v112
	s_waitcnt lgkmcnt(3)
	v_add_f32_e32 v1, v1, v97
	ds_bpermute_b32 v97, v204, v1
	s_waitcnt lgkmcnt(3)
	v_add_f32_e32 v111, v111, v115
	s_waitcnt lgkmcnt(2)
	v_add_f32_e32 v0, v0, v98
	s_waitcnt lgkmcnt(1)
	v_add_f32_e32 v112, v112, v113
	ds_bpermute_b32 v98, v206, v0
	ds_bpermute_b32 v113, v206, v112
	s_waitcnt lgkmcnt(2)
	v_add_f32_e32 v1, v1, v97
	v_fmamk_f32 v97, v99, 0xbc800000, v2
	v_fmamk_f32 v2, v99, 0xbc800000, v18
	v_mul_f32_e32 v18, v2, v2
	s_waitcnt lgkmcnt(1)
	v_add_f32_e32 v0, v0, v98
	v_fmac_f32_e32 v18, v97, v97
	v_fmamk_f32 v98, v100, 0xbc800000, v3
	v_fmamk_f32 v3, v100, 0xbc800000, v19
	s_waitcnt lgkmcnt(0)
	v_add_f32_e32 v112, v112, v113
	ds_bpermute_b32 v113, v205, v1
	ds_bpermute_b32 v99, v202, v18
	v_mul_f32_e32 v19, v3, v3
	v_fmac_f32_e32 v19, v98, v98
	ds_bpermute_b32 v100, v202, v19
	s_waitcnt lgkmcnt(2)
	v_add_f32_e32 v1, v1, v113
	s_waitcnt lgkmcnt(1)
	v_add_f32_e32 v99, v18, v99
	ds_bpermute_b32 v113, v206, v1
	ds_bpermute_b32 v115, v203, v99
	s_waitcnt lgkmcnt(2)
	v_add_f32_e32 v19, v19, v100
	ds_bpermute_b32 v100, v203, v19
	v_fmamk_f32 v0, v0, 0x3c800000, v228
	v_rsq_f32_e32 v18, v0
	s_waitcnt lgkmcnt(2)
	v_add_f32_e32 v0, v1, v113
	s_waitcnt lgkmcnt(1)
	v_add_f32_e32 v1, v99, v115
	ds_bpermute_b32 v99, v204, v1
	s_waitcnt lgkmcnt(1)
	v_add_f32_e32 v100, v19, v100
	ds_bpermute_b32 v113, v204, v100
	v_fmamk_f32 v0, v0, 0x3c800000, v228
	v_rsq_f32_e32 v19, v0
	s_waitcnt lgkmcnt(1)
	v_add_f32_e32 v0, v1, v99
	ds_bpermute_b32 v1, v205, v0
	v_fmamk_f32 v99, v101, 0xbc800000, v4
	v_fmamk_f32 v4, v101, 0xbc800000, v20
	s_waitcnt lgkmcnt(1)
	v_add_f32_e32 v100, v100, v113
	v_mul_f32_e32 v20, v4, v4
	ds_bpermute_b32 v113, v205, v100
	v_fmac_f32_e32 v20, v99, v99
	ds_bpermute_b32 v101, v202, v20
	s_waitcnt lgkmcnt(2)
	v_add_f32_e32 v0, v0, v1
	ds_bpermute_b32 v1, v206, v0
	s_waitcnt lgkmcnt(2)
	v_add_f32_e32 v100, v100, v113
	ds_bpermute_b32 v113, v206, v100
	s_waitcnt lgkmcnt(2)
	v_add_f32_e32 v101, v20, v101
	ds_bpermute_b32 v115, v203, v101
	s_waitcnt lgkmcnt(2)
	v_add_f32_e32 v0, v0, v1
	v_fmamk_f32 v0, v0, 0x3c800000, v228
	v_rsq_f32_e32 v20, v0
	s_waitcnt lgkmcnt(1)
	v_add_f32_e32 v0, v100, v113
	v_fmamk_f32 v100, v102, 0xbc800000, v5
	v_fmamk_f32 v5, v102, 0xbc800000, v21
	s_waitcnt lgkmcnt(0)
	v_add_f32_e32 v1, v101, v115
	v_mul_f32_e32 v102, v5, v5
	ds_bpermute_b32 v101, v204, v1
	v_fmac_f32_e32 v102, v100, v100
	ds_bpermute_b32 v113, v202, v102
	v_fmamk_f32 v0, v0, 0x3c800000, v228
	v_rsq_f32_e32 v21, v0
	s_waitcnt lgkmcnt(1)
	v_add_f32_e32 v0, v1, v101
	v_fmamk_f32 v101, v103, 0xbc800000, v6
	v_fmamk_f32 v6, v103, 0xbc800000, v22
	s_waitcnt lgkmcnt(0)
	v_add_f32_e32 v102, v102, v113
	v_mul_f32_e32 v22, v6, v6
	ds_bpermute_b32 v1, v205, v0
	ds_bpermute_b32 v113, v203, v102
	v_fmac_f32_e32 v22, v101, v101
	ds_bpermute_b32 v103, v202, v22
	v_mad_u64_u32 v[78:79], s[0:1], v40, s60, v[90:91]
	s_waitcnt lgkmcnt(2)
	v_add_f32_e32 v0, v0, v1
	s_waitcnt lgkmcnt(1)
	v_add_f32_e32 v102, v102, v113
	ds_bpermute_b32 v1, v206, v0
	ds_bpermute_b32 v113, v204, v102
	s_waitcnt lgkmcnt(2)
	v_add_f32_e32 v22, v22, v103
	ds_bpermute_b32 v103, v203, v22
	v_mad_u64_u32 v[80:81], s[0:1], v38, s60, v[90:91]
	s_waitcnt lgkmcnt(2)
	v_add_f32_e32 v0, v0, v1
	s_waitcnt lgkmcnt(1)
	v_add_f32_e32 v1, v102, v113
	v_fmamk_f32 v102, v104, 0xbc800000, v7
	v_fmamk_f32 v7, v104, 0xbc800000, v23
	s_waitcnt lgkmcnt(0)
	v_add_f32_e32 v22, v22, v103
	v_mul_f32_e32 v23, v7, v7
	ds_bpermute_b32 v113, v205, v1
	ds_bpermute_b32 v103, v204, v22
	v_fmac_f32_e32 v23, v102, v102
	ds_bpermute_b32 v104, v202, v23
	v_fmamk_f32 v0, v0, 0x3c800000, v228
	s_waitcnt lgkmcnt(2)
	v_add_f32_e32 v1, v1, v113
	s_waitcnt lgkmcnt(1)
	v_add_f32_e32 v103, v22, v103
	ds_bpermute_b32 v113, v206, v1
	ds_bpermute_b32 v115, v205, v103
	s_waitcnt lgkmcnt(2)
	v_add_f32_e32 v23, v23, v104
	ds_bpermute_b32 v104, v203, v23
	v_rsq_f32_e32 v22, v0
	s_waitcnt lgkmcnt(2)
	v_add_f32_e32 v0, v1, v113
	s_waitcnt lgkmcnt(1)
	v_add_f32_e32 v1, v103, v115
	ds_bpermute_b32 v103, v206, v1
	s_waitcnt lgkmcnt(1)
	v_add_f32_e32 v104, v23, v104
	ds_bpermute_b32 v113, v204, v104
	v_fmamk_f32 v0, v0, 0x3c800000, v228
	v_rsq_f32_e32 v23, v0
	s_waitcnt lgkmcnt(1)
	v_add_f32_e32 v0, v1, v103
	v_fmamk_f32 v103, v105, 0xbc800000, v8
	v_fmamk_f32 v8, v105, 0xbc800000, v24
	s_waitcnt lgkmcnt(0)
	v_add_f32_e32 v1, v104, v113
	v_mul_f32_e32 v24, v8, v8
	v_fmamk_f32 v104, v106, 0xbc800000, v9
	v_fmamk_f32 v9, v106, 0xbc800000, v25
	v_fmac_f32_e32 v24, v103, v103
	v_mul_f32_e32 v25, v9, v9
	ds_bpermute_b32 v113, v205, v1
	ds_bpermute_b32 v105, v202, v24
	v_fmac_f32_e32 v25, v104, v104
	ds_bpermute_b32 v106, v202, v25
	v_fmamk_f32 v0, v0, 0x3c800000, v228
	s_waitcnt lgkmcnt(2)
	v_add_f32_e32 v1, v1, v113
	s_waitcnt lgkmcnt(1)
	v_add_f32_e32 v105, v24, v105
	ds_bpermute_b32 v113, v206, v1
	ds_bpermute_b32 v115, v203, v105
	s_waitcnt lgkmcnt(2)
	v_add_f32_e32 v25, v25, v106
	ds_bpermute_b32 v106, v203, v25
	v_rsq_f32_e32 v24, v0
	s_waitcnt lgkmcnt(2)
	v_add_f32_e32 v0, v1, v113
	s_waitcnt lgkmcnt(1)
	v_add_f32_e32 v1, v105, v115
	ds_bpermute_b32 v105, v204, v1
	s_waitcnt lgkmcnt(1)
	v_add_f32_e32 v106, v25, v106
	ds_bpermute_b32 v113, v204, v106
	v_fmamk_f32 v0, v0, 0x3c800000, v228
	v_rsq_f32_e32 v25, v0
	s_waitcnt lgkmcnt(1)
	v_add_f32_e32 v0, v1, v105
	ds_bpermute_b32 v1, v205, v0
	s_waitcnt lgkmcnt(1)
	v_add_f32_e32 v105, v106, v113
	v_fmamk_f32 v113, v107, 0xbc800000, v10
	v_fmamk_f32 v10, v107, 0xbc800000, v26
	v_mul_f32_e32 v26, v10, v10
	ds_bpermute_b32 v106, v205, v105
	v_fmac_f32_e32 v26, v113, v113
	ds_bpermute_b32 v107, v202, v26
	s_waitcnt lgkmcnt(2)
	v_add_f32_e32 v0, v0, v1
	ds_bpermute_b32 v1, v206, v0
	s_waitcnt lgkmcnt(2)
	v_add_f32_e32 v105, v105, v106
	ds_bpermute_b32 v106, v206, v105
	s_waitcnt lgkmcnt(2)
	v_add_f32_e32 v107, v26, v107
	ds_bpermute_b32 v115, v203, v107
	s_waitcnt lgkmcnt(2)
	v_add_f32_e32 v0, v0, v1
	v_fmamk_f32 v0, v0, 0x3c800000, v228
	v_rsq_f32_e32 v26, v0
	s_waitcnt lgkmcnt(1)
	v_add_f32_e32 v0, v105, v106
	v_fmamk_f32 v106, v108, 0xbc800000, v11
	v_fmamk_f32 v11, v108, 0xbc800000, v27
	s_waitcnt lgkmcnt(0)
	v_add_f32_e32 v1, v107, v115
	v_mul_f32_e32 v107, v11, v11
	v_fmac_f32_e32 v107, v106, v106
	ds_bpermute_b32 v105, v204, v1
	ds_bpermute_b32 v108, v202, v107
	v_mad_u64_u32 v[82:83], s[0:1], v36, s60, v[90:91]
	v_mad_u64_u32 v[84:85], s[0:1], v34, s60, v[90:91]
	v_mad_u64_u32 v[86:87], s[0:1], v32, s60, v[90:91]
	v_mad_u64_u32 v[88:89], s[0:1], v58, s60, v[90:91]
	v_mad_u64_u32 v[90:91], s[0:1], v60, s60, v[90:91]
	v_fmamk_f32 v0, v0, 0x3c800000, v228
	v_readlane_b32 s0, v255, 26
	v_rsq_f32_e32 v27, v0
	s_waitcnt lgkmcnt(1)
	v_add_f32_e32 v0, v1, v105
	s_waitcnt lgkmcnt(0)
	v_add_f32_e32 v105, v107, v108
	v_fmamk_f32 v108, v109, 0xbc800000, v12
	v_fmamk_f32 v12, v109, 0xbc800000, v28
	v_or_b32_e32 v116, s0, v191
	v_mad_i32_i24 v93, v63, s60, v93
	v_mul_f32_e32 v28, v12, v12
	v_lshlrev_b32_e32 v116, 2, v116
	v_fmac_f32_e32 v28, v108, v108
	global_load_ushort v115, v[92:93], off offset:1536
	global_load_dword v117, v116, s[2:3]
	ds_bpermute_b32 v109, v202, v28
	ds_bpermute_b32 v1, v205, v0
	ds_bpermute_b32 v107, v203, v105
	v_fmamk_f32 v13, v110, 0xbc800000, v13
	v_fmac_f32_e32 v31, 0xbc800000, v112
	s_waitcnt lgkmcnt(2)
	v_add_f32_e32 v28, v28, v109
	ds_bpermute_b32 v109, v203, v28
	s_waitcnt lgkmcnt(2)
	v_add_f32_e32 v0, v0, v1
	s_waitcnt lgkmcnt(1)
	v_add_f32_e32 v105, v105, v107
	ds_bpermute_b32 v1, v206, v0
	ds_bpermute_b32 v107, v204, v105
	s_waitcnt lgkmcnt(2)
	v_add_f32_e32 v28, v28, v109
	v_fmamk_f32 v109, v110, 0xbc800000, v29
	v_mul_f32_e32 v29, v109, v109
	s_waitcnt lgkmcnt(1)
	v_add_f32_e32 v0, v0, v1
	s_waitcnt lgkmcnt(0)
	v_add_f32_e32 v1, v105, v107
	v_fmac_f32_e32 v29, v13, v13
	ds_bpermute_b32 v105, v205, v1
	ds_bpermute_b32 v107, v204, v28
	ds_bpermute_b32 v110, v202, v29
	v_fmamk_f32 v0, v0, 0x3c800000, v228
	v_rsq_f32_e32 v118, v0
	s_waitcnt lgkmcnt(2)
	v_add_f32_e32 v1, v1, v105
	s_waitcnt lgkmcnt(1)
	v_add_f32_e32 v28, v28, v107
	s_waitcnt lgkmcnt(0)
	v_add_f32_e32 v29, v29, v110
	ds_bpermute_b32 v105, v206, v1
	ds_bpermute_b32 v107, v205, v28
	ds_bpermute_b32 v110, v203, v29
	v_fmamk_f32 v14, v111, 0xbc800000, v14
	v_fmamk_f32 v30, v111, 0xbc800000, v30
	s_waitcnt lgkmcnt(2)
	v_add_f32_e32 v0, v1, v105
	s_waitcnt lgkmcnt(1)
	v_add_f32_e32 v1, v28, v107
	s_waitcnt lgkmcnt(0)
	v_add_f32_e32 v29, v29, v110
	ds_bpermute_b32 v28, v206, v1
	ds_bpermute_b32 v105, v204, v29
	v_fmac_f32_e32 v15, 0xbc800000, v112
	v_mul_f32_e32 v111, v31, v31
	v_fmac_f32_e32 v111, v15, v15
	ds_bpermute_b32 v119, v202, v111
	v_fmamk_f32 v0, v0, 0x3c800000, v228
	v_rsq_f32_e32 v107, v0
	s_waitcnt lgkmcnt(2)
	v_add_f32_e32 v0, v1, v28
	s_waitcnt lgkmcnt(1)
	v_add_f32_e32 v1, v29, v105
	v_mul_f32_e32 v29, v30, v30
	v_fmac_f32_e32 v29, v14, v14
	ds_bpermute_b32 v28, v205, v1
	ds_bpermute_b32 v110, v202, v29
	s_waitcnt lgkmcnt(2)
	v_add_f32_e32 v111, v111, v119
	ds_bpermute_b32 v119, v203, v111
	v_mad_i32_i24 v95, v63, s60, v95
	global_load_ushort v105, v[94:95], off offset:1536
	s_waitcnt lgkmcnt(2)
	v_add_f32_e32 v1, v1, v28
	s_waitcnt lgkmcnt(1)
	v_add_f32_e32 v28, v29, v110
	v_fmamk_f32 v0, v0, 0x3c800000, v228
	ds_bpermute_b32 v29, v203, v28
	v_rsq_f32_e32 v123, v0
	s_waitcnt lgkmcnt(1)
	v_add_f32_e32 v0, v111, v119
	v_mad_i32_i24 v65, v63, s60, v65
	ds_bpermute_b32 v111, v204, v0
	global_load_ushort v112, v[64:65], off offset:1536
	s_waitcnt lgkmcnt(1)
	v_add_f32_e32 v28, v28, v29
	v_mad_i32_i24 v67, v63, s60, v67
	ds_bpermute_b32 v110, v206, v1
	ds_bpermute_b32 v29, v204, v28
	global_load_ushort v122, v[66:67], off offset:1536
	s_waitcnt lgkmcnt(2)
	v_add_f32_e32 v0, v0, v111
	ds_bpermute_b32 v111, v205, v0
	v_mad_i32_i24 v69, v63, s60, v69
	s_waitcnt lgkmcnt(2)
	v_add_f32_e32 v1, v1, v110
	s_waitcnt lgkmcnt(1)
	v_add_f32_e32 v28, v28, v29
	global_load_ushort v110, v[68:69], off offset:1536
	ds_bpermute_b32 v29, v205, v28
	v_fmamk_f32 v1, v1, 0x3c800000, v228
	s_waitcnt lgkmcnt(1)
	v_add_f32_e32 v0, v0, v111
	v_mad_i32_i24 v71, v63, s60, v71
	v_rsq_f32_e32 v119, v1
	ds_bpermute_b32 v1, v206, v0
	global_load_ushort v111, v[70:71], off offset:1536
	s_waitcnt lgkmcnt(1)
	v_add_f32_e32 v28, v28, v29
	ds_bpermute_b32 v29, v206, v28
	v_readlane_b32 s0, v254, 13
	s_waitcnt lgkmcnt(1)
	v_add_f32_e32 v0, v0, v1
	v_mad_i32_i24 v73, v63, s60, v73
	v_fmamk_f32 v0, v0, 0x3c800000, v228
	v_readlane_b32 s1, v254, 14
	v_rsq_f32_e32 v125, v0
	v_mad_i32_i24 v75, v63, s60, v75
	v_lshl_add_u64 v[0:1], s[0:1], 0, v[120:121]
	global_load_ushort v120, v[72:73], off offset:1536
	s_nop 0
	global_load_ushort v92, v[92:93], off offset:1600
	s_nop 0
	global_load_ushort v93, v[94:95], off offset:1600
	s_waitcnt lgkmcnt(0)
	v_add_f32_e32 v28, v28, v29
	v_mul_f32_e32 v29, v114, v18
	global_load_ushort v114, v[74:75], off offset:1536
	v_fmamk_f32 v28, v28, 0x3c800000, v228
	v_rsq_f32_e32 v124, v28
	s_waitcnt vmcnt(10)
	v_lshlrev_b32_e32 v28, 16, v115
	s_waitcnt vmcnt(9)
	v_mul_f32_e32 v29, v29, v117
	v_mul_f32_e32 v28, v29, v28
	v_mad_i32_i24 v77, v63, s60, v77
	v_mad_i32_i24 v79, v63, s60, v79
	v_mad_i32_i24 v81, v63, s60, v81
	v_mad_i32_i24 v83, v63, s60, v83
	v_bfe_u32 v29, v28, 16, 1
	v_mov_b32_e32 v57, v63
	v_mov_b32_e32 v55, v63
	v_mov_b32_e32 v53, v63
	v_mov_b32_e32 v51, v63
	v_mov_b32_e32 v49, v63
	v_mov_b32_e32 v47, v63
	v_mov_b32_e32 v45, v63
	v_mov_b32_e32 v43, v63
	v_mov_b32_e32 v41, v63
	v_mov_b32_e32 v39, v63
	v_mov_b32_e32 v37, v63
	v_mov_b32_e32 v35, v63
	v_mad_i32_i24 v85, v63, s60, v85
	v_mov_b32_e32 v33, v63
	v_mad_i32_i24 v87, v63, s60, v87
	v_mov_b32_e32 v59, v63
	v_mad_i32_i24 v89, v63, s60, v89
	v_mov_b32_e32 v61, v63
	v_mad_i32_i24 v91, v63, s60, v91
	global_load_dword v94, v116, s[2:3] offset:128
	v_add3_u32 v95, v28, v29, s96
	v_lshlrev_b64 v[28:29], 11, v[62:63]
	global_load_ushort v62, v[64:65], off offset:1600
	global_load_ushort v63, v[66:67], off offset:1600
	s_nop 0
	global_load_ushort v64, v[68:69], off offset:1600
	global_load_ushort v65, v[70:71], off offset:1600
	global_load_ushort v66, v[72:73], off offset:1600
	global_load_ushort v67, v[74:75], off offset:1600
	s_nop 0
	global_load_ushort v68, v[76:77], off offset:1536
	global_load_ushort v69, v[78:79], off offset:1536
	global_load_ushort v70, v[80:81], off offset:1536
	global_load_ushort v71, v[82:83], off offset:1536
	global_load_ushort v72, v[76:77], off offset:1600
	global_load_ushort v73, v[78:79], off offset:1600
	global_load_ushort v74, v[80:81], off offset:1600
	global_load_ushort v75, v[82:83], off offset:1600
	s_nop 0
	global_load_ushort v76, v[84:85], off offset:1536
	global_load_ushort v77, v[86:87], off offset:1536
	global_load_ushort v78, v[88:89], off offset:1536
	global_load_ushort v79, v[90:91], off offset:1536
	global_load_ushort v80, v[84:85], off offset:1600
	global_load_ushort v81, v[86:87], off offset:1600
	global_load_ushort v82, v[88:89], off offset:1600
	global_load_ushort v83, v[90:91], off offset:1600
	v_mul_f32_e32 v85, v96, v19
	v_mul_f32_e32 v85, v85, v117
	v_lshlrev_b64 v[56:57], 11, v[56:57]
	v_lshl_add_u64 v[56:57], v[0:1], 0, v[56:57]
	v_lshlrev_b64 v[54:55], 11, v[54:55]
	s_waitcnt vmcnt(31)
	v_lshlrev_b32_e32 v84, 16, v105
	v_mul_f32_e32 v84, v85, v84
	v_bfe_u32 v85, v84, 16, 1
	v_add3_u32 v84, v84, v85, s96
	v_mul_f32_e32 v85, v97, v20
	global_store_short_d16_hi v[56:57], v84, off
	v_mul_f32_e32 v85, v85, v117
	v_lshl_add_u64 v[54:55], v[0:1], 0, v[54:55]
	v_lshlrev_b64 v[52:53], 11, v[52:53]
	s_waitcnt vmcnt(31)
	v_lshlrev_b32_e32 v84, 16, v112
	v_mul_f32_e32 v84, v85, v84
	v_bfe_u32 v85, v84, 16, 1
	v_add3_u32 v84, v84, v85, s96
	v_mul_f32_e32 v85, v98, v21
	global_store_short_d16_hi v[54:55], v84, off
	s_waitcnt vmcnt(31)
	v_lshlrev_b32_e32 v84, 16, v122
	v_mul_f32_e32 v85, v85, v117
	v_mul_f32_e32 v84, v85, v84
	v_bfe_u32 v85, v84, 16, 1
	v_add3_u32 v84, v84, v85, s96
	v_lshl_add_u64 v[52:53], v[0:1], 0, v[52:53]
	v_mul_f32_e32 v85, v99, v22
	global_store_short_d16_hi v[52:53], v84, off
	s_waitcnt vmcnt(31)
	v_lshlrev_b32_e32 v84, 16, v110
	v_mul_f32_e32 v85, v85, v117
	v_mul_f32_e32 v84, v85, v84
	v_bfe_u32 v85, v84, 16, 1
	v_lshlrev_b64 v[50:51], 11, v[50:51]
	v_add3_u32 v84, v84, v85, s96
	v_lshl_add_u64 v[50:51], v[0:1], 0, v[50:51]
	v_mul_f32_e32 v85, v100, v23
	global_store_short_d16_hi v[50:51], v84, off
	s_waitcnt vmcnt(31)
	v_lshlrev_b32_e32 v84, 16, v111
	v_mul_f32_e32 v85, v85, v117
	v_mul_f32_e32 v84, v85, v84
	v_bfe_u32 v85, v84, 16, 1
	v_lshlrev_b64 v[48:49], 11, v[48:49]
	v_add3_u32 v84, v84, v85, s96
	v_lshl_add_u64 v[48:49], v[0:1], 0, v[48:49]
	v_mul_f32_e32 v85, v101, v24
	global_store_short_d16_hi v[48:49], v84, off
	s_waitcnt vmcnt(31)
	v_lshlrev_b32_e32 v84, 16, v120
	v_mul_f32_e32 v85, v85, v117
	v_mul_f32_e32 v84, v85, v84
	v_bfe_u32 v85, v84, 16, 1
	v_lshlrev_b64 v[46:47], 11, v[46:47]
	v_add3_u32 v84, v84, v85, s96
	v_lshl_add_u64 v[46:47], v[0:1], 0, v[46:47]
	v_mul_f32_e32 v85, v102, v25
	global_store_short_d16_hi v[46:47], v84, off
	s_waitcnt vmcnt(29)
	v_lshlrev_b32_e32 v84, 16, v114
	v_mul_f32_e32 v85, v85, v117
	v_mul_f32_e32 v84, v85, v84
	v_bfe_u32 v85, v84, 16, 1
	v_lshlrev_b64 v[44:45], 11, v[44:45]
	v_add3_u32 v84, v84, v85, s96
	v_lshl_add_u64 v[44:45], v[0:1], 0, v[44:45]
	global_store_short_d16_hi v[44:45], v84, off
	v_mul_f32_e32 v84, v103, v26
	s_waitcnt vmcnt(22)
	v_lshlrev_b32_e32 v68, 16, v68
	v_mul_f32_e32 v84, v84, v117
	v_mul_f32_e32 v68, v84, v68
	v_bfe_u32 v84, v68, 16, 1
	v_lshlrev_b64 v[42:43], 11, v[42:43]
	v_add3_u32 v68, v68, v84, s96
	v_lshl_add_u64 v[42:43], v[0:1], 0, v[42:43]
	global_store_short_d16_hi v[42:43], v68, off
	s_waitcnt vmcnt(22)
	v_lshlrev_b32_e32 v68, 16, v69
	v_mul_f32_e32 v69, v104, v27
	v_mul_f32_e32 v69, v69, v117
	v_mul_f32_e32 v68, v69, v68
	v_bfe_u32 v69, v68, 16, 1
	v_lshlrev_b64 v[40:41], 11, v[40:41]
	v_add3_u32 v68, v68, v69, s96
	v_lshl_add_u64 v[40:41], v[0:1], 0, v[40:41]
	v_mul_f32_e32 v69, v113, v118
	global_store_short_d16_hi v[40:41], v68, off
	s_waitcnt vmcnt(22)
	v_lshlrev_b32_e32 v68, 16, v70
	v_mul_f32_e32 v69, v69, v117
	v_mul_f32_e32 v68, v69, v68
	v_bfe_u32 v69, v68, 16, 1
	v_lshlrev_b64 v[38:39], 11, v[38:39]
	v_add3_u32 v68, v68, v69, s96
	v_lshl_add_u64 v[38:39], v[0:1], 0, v[38:39]
	v_mul_f32_e32 v69, v106, v107
	global_store_short_d16_hi v[38:39], v68, off
	s_waitcnt vmcnt(22)
	v_lshlrev_b32_e32 v68, 16, v71
	v_mul_f32_e32 v69, v69, v117
	v_mul_f32_e32 v68, v69, v68
	v_bfe_u32 v69, v68, 16, 1
	v_lshlrev_b64 v[36:37], 11, v[36:37]
	v_add3_u32 v68, v68, v69, s96
	v_lshl_add_u64 v[36:37], v[0:1], 0, v[36:37]
	v_mul_f32_e32 v69, v108, v123
	global_store_short_d16_hi v[36:37], v68, off
	s_waitcnt vmcnt(18)
	v_lshlrev_b32_e32 v68, 16, v76
	v_mul_f32_e32 v69, v69, v117
	v_mul_f32_e32 v68, v69, v68
	v_bfe_u32 v69, v68, 16, 1
	v_lshlrev_b64 v[34:35], 11, v[34:35]
	v_add3_u32 v68, v68, v69, s96
	v_lshl_add_u64 v[34:35], v[0:1], 0, v[34:35]
	v_mul_f32_e32 v13, v13, v119
	global_store_short_d16_hi v[34:35], v68, off
	s_waitcnt vmcnt(18)
	v_lshlrev_b32_e32 v68, 16, v77
	v_mul_f32_e32 v13, v13, v117
	v_mul_f32_e32 v13, v13, v68
	v_bfe_u32 v68, v13, 16, 1
	v_lshlrev_b64 v[32:33], 11, v[32:33]
	v_add3_u32 v13, v13, v68, s96
	v_lshl_add_u64 v[32:33], v[0:1], 0, v[32:33]
	v_mul_f32_e32 v14, v14, v124
	global_store_short_d16_hi v[32:33], v13, off
	s_waitcnt vmcnt(18)
	v_lshlrev_b32_e32 v13, 16, v78
	v_mul_f32_e32 v14, v117, v14
	v_mul_f32_e32 v13, v14, v13
	v_bfe_u32 v14, v13, 16, 1
	v_lshlrev_b64 v[58:59], 11, v[58:59]
	v_add3_u32 v13, v13, v14, s96
	v_lshl_add_u64 v[58:59], v[0:1], 0, v[58:59]
	v_mul_f32_e32 v14, v15, v125
	global_store_short_d16_hi v[58:59], v13, off
	s_waitcnt vmcnt(18)
	v_lshlrev_b32_e32 v13, 16, v79
	v_mul_f32_e32 v14, v117, v14
	v_mul_f32_e32 v13, v14, v13
	v_bfe_u32 v14, v13, 16, 1
	v_add3_u32 v13, v13, v14, s96
	v_lshlrev_b64 v[14:15], 11, v[60:61]
	v_lshl_add_u64 v[28:29], v[0:1], 0, v[28:29]
	v_lshl_add_u64 v[0:1], v[0:1], 0, v[14:15]
	v_mul_f32_e32 v14, v16, v18
	global_store_short_d16_hi v[0:1], v13, off
	v_lshlrev_b32_e32 v13, 16, v92
	v_mul_f32_e32 v14, v14, v94
	v_mul_f32_e32 v13, v14, v13
	v_bfe_u32 v14, v13, 16, 1
	v_add3_u32 v13, v13, v14, s96
	v_mul_f32_e32 v14, v17, v19
	global_store_short_d16_hi v[28:29], v13, off offset:64
	v_lshlrev_b32_e32 v13, 16, v93
	v_mul_f32_e32 v14, v14, v94
	v_mul_f32_e32 v13, v14, v13
	v_bfe_u32 v14, v13, 16, 1
	v_add3_u32 v13, v13, v14, s96
	v_mul_f32_e32 v2, v2, v20
	global_store_short_d16_hi v[56:57], v13, off offset:64
	v_lshlrev_b32_e32 v13, 16, v62
	v_mul_f32_e32 v2, v2, v94
	v_mul_f32_e32 v2, v2, v13
	v_bfe_u32 v13, v2, 16, 1
	v_add3_u32 v2, v2, v13, s96
	v_mul_f32_e32 v3, v3, v21
	global_store_short_d16_hi v[54:55], v2, off offset:64
	v_lshlrev_b32_e32 v2, 16, v63
	v_mul_f32_e32 v3, v3, v94
	v_mul_f32_e32 v2, v3, v2
	v_bfe_u32 v3, v2, 16, 1
	v_add3_u32 v2, v2, v3, s96
	v_mul_f32_e32 v3, v4, v22
	global_store_short_d16_hi v[52:53], v2, off offset:64
	v_lshlrev_b32_e32 v2, 16, v64
	v_mul_f32_e32 v3, v3, v94
	v_mul_f32_e32 v2, v3, v2
	v_bfe_u32 v3, v2, 16, 1
	v_add3_u32 v2, v2, v3, s96
	v_mul_f32_e32 v3, v5, v23
	global_store_short_d16_hi v[50:51], v2, off offset:64
	v_lshlrev_b32_e32 v2, 16, v65
	v_mul_f32_e32 v3, v3, v94
	v_mul_f32_e32 v2, v3, v2
	v_bfe_u32 v3, v2, 16, 1
	v_add3_u32 v2, v2, v3, s96
	v_mul_f32_e32 v3, v6, v24
	global_store_short_d16_hi v[48:49], v2, off offset:64
	v_lshlrev_b32_e32 v2, 16, v66
	v_mul_f32_e32 v3, v3, v94
	v_mul_f32_e32 v2, v3, v2
	v_bfe_u32 v3, v2, 16, 1
	v_add3_u32 v2, v2, v3, s96
	v_mul_f32_e32 v3, v7, v25
	global_store_short_d16_hi v[46:47], v2, off offset:64
	v_lshlrev_b32_e32 v2, 16, v67
	v_mul_f32_e32 v3, v3, v94
	v_mul_f32_e32 v2, v3, v2
	v_bfe_u32 v3, v2, 16, 1
	v_add3_u32 v2, v2, v3, s96
	v_mul_f32_e32 v3, v8, v26
	global_store_short_d16_hi v[44:45], v2, off offset:64
	v_lshlrev_b32_e32 v2, 16, v72
	v_mul_f32_e32 v3, v3, v94
	v_mul_f32_e32 v2, v3, v2
	v_bfe_u32 v3, v2, 16, 1
	v_add3_u32 v2, v2, v3, s96
	v_mul_f32_e32 v3, v9, v27
	global_store_short_d16_hi v[42:43], v2, off offset:64
	v_lshlrev_b32_e32 v2, 16, v73
	v_mul_f32_e32 v3, v3, v94
	v_mul_f32_e32 v2, v3, v2
	v_bfe_u32 v3, v2, 16, 1
	v_add3_u32 v2, v2, v3, s96
	v_mul_f32_e32 v3, v10, v118
	global_store_short_d16_hi v[40:41], v2, off offset:64
	v_lshlrev_b32_e32 v2, 16, v74
	v_mul_f32_e32 v3, v3, v94
	v_mul_f32_e32 v2, v3, v2
	v_bfe_u32 v3, v2, 16, 1
	v_add3_u32 v2, v2, v3, s96
	v_mul_f32_e32 v3, v11, v107
	global_store_short_d16_hi v[38:39], v2, off offset:64
	v_lshlrev_b32_e32 v2, 16, v75
	v_mul_f32_e32 v3, v3, v94
	v_mul_f32_e32 v2, v3, v2
	v_bfe_u32 v3, v2, 16, 1
	v_add3_u32 v2, v2, v3, s96
	v_mul_f32_e32 v3, v12, v123
	global_store_short_d16_hi v[36:37], v2, off offset:64
	s_waitcnt vmcnt(30)
	v_lshlrev_b32_e32 v2, 16, v80
	v_mul_f32_e32 v3, v3, v94
	v_mul_f32_e32 v2, v3, v2
	v_bfe_u32 v3, v2, 16, 1
	v_add3_u32 v2, v2, v3, s96
	v_mul_f32_e32 v3, v109, v119
	global_store_short_d16_hi v[34:35], v2, off offset:64
	s_waitcnt vmcnt(30)
	v_lshlrev_b32_e32 v2, 16, v81
	v_mul_f32_e32 v3, v3, v94
	v_mul_f32_e32 v2, v3, v2
	v_bfe_u32 v3, v2, 16, 1
	v_add3_u32 v2, v2, v3, s96
	v_mul_f32_e32 v3, v30, v124
	global_store_short_d16_hi v[32:33], v2, off offset:64
	s_waitcnt vmcnt(30)
	v_lshlrev_b32_e32 v2, 16, v82
	v_mul_f32_e32 v3, v3, v94
	v_mul_f32_e32 v2, v3, v2
	v_bfe_u32 v3, v2, 16, 1
	v_add3_u32 v2, v2, v3, s96
	v_mul_f32_e32 v3, v31, v125
	global_store_short_d16_hi v[58:59], v2, off offset:64
	s_waitcnt vmcnt(30)
	v_lshlrev_b32_e32 v2, 16, v83
	v_mul_f32_e32 v3, v3, v94
	v_mul_f32_e32 v2, v3, v2
	v_bfe_u32 v3, v2, 16, 1
	v_add3_u32 v2, v2, v3, s96
	s_movk_i32 s22, 0x100
	s_mov_b64 s[0:1], 0
	s_and_b64 vcc, exec, s[10:11]
	global_store_short_d16_hi v[28:29], v95, off
	global_store_short_d16_hi v[0:1], v2, off offset:64
	s_barrier
	s_cbranch_vccnz .LBB0_902

.LBB0_997:
	s_or_b64 exec, exec, s[10:11]
	v_mov_b32_e32 v0, 2
	v_lshlrev_b32_sdwa v152, v0, v8 dst_sel:DWORD dst_unused:UNUSED_PAD src0_sel:DWORD src1_sel:BYTE_0
	v_lshl_add_u64 v[28:29], s[0:1], 0, v[152:153]
	v_add_co_u32_e32 v12, vcc, 0x1000, v28
	s_movk_i32 s10, 0x2000
	s_nop 0
	v_addc_co_u32_e32 v13, vcc, 0, v29, vcc
	global_load_dword v3, v152, s[0:1]
	global_load_dword v2, v152, s[0:1] offset:1024
	global_load_dword v1, v152, s[0:1] offset:2048
	global_load_dword v0, v152, s[0:1] offset:3072
	global_load_dword v7, v[12:13], off
	global_load_dword v6, v[12:13], off offset:1024
	global_load_dword v5, v[12:13], off offset:2048
	global_load_dword v4, v[12:13], off offset:3072
	v_add_co_u32_e32 v12, vcc, s10, v28
	s_movk_i32 s10, 0x3000
	s_nop 0
	v_addc_co_u32_e32 v13, vcc, 0, v29, vcc
	v_add_co_u32_e32 v20, vcc, s10, v28
	s_movk_i32 s10, 0x4000
	s_nop 0
	v_addc_co_u32_e32 v21, vcc, 0, v29, vcc
	v_add_co_u32_e32 v24, vcc, s10, v28
	s_movk_i32 s10, 0x5000
	s_nop 0
	v_addc_co_u32_e32 v25, vcc, 0, v29, vcc
	v_add_co_u32_e32 v30, vcc, s10, v28
	s_movk_i32 s10, 0x6000
	s_nop 0
	v_addc_co_u32_e32 v31, vcc, 0, v29, vcc
	v_add_co_u32_e32 v32, vcc, s10, v28
	s_movk_i32 s10, 0x7000
	s_nop 0
	v_addc_co_u32_e32 v33, vcc, 0, v29, vcc
	v_add_co_u32_e32 v36, vcc, s10, v28
	global_load_dword v18, v[20:21], off offset:-4096
	global_load_dword v17, v[12:13], off offset:1024
	global_load_dword v16, v[12:13], off offset:2048
	global_load_dword v15, v[12:13], off offset:3072
	global_load_dword v14, v[20:21], off
	s_nop 0
	global_load_dword v13, v[20:21], off offset:1024
	global_load_dword v12, v[20:21], off offset:2048
	global_load_dword v9, v[20:21], off offset:3072
	v_addc_co_u32_e32 v37, vcc, 0, v29, vcc
	global_load_dword v19, v[30:31], off offset:-4096
	global_load_dword v22, v[24:25], off offset:1024
	global_load_dword v21, v[24:25], off offset:2048
	global_load_dword v20, v[24:25], off offset:3072
	global_load_dword v26, v[30:31], off
	s_nop 0
	global_load_dword v25, v[30:31], off offset:1024
	global_load_dword v24, v[30:31], off offset:2048
	global_load_dword v23, v[30:31], off offset:3072
	global_load_dword v28, v[36:37], off offset:-4096
	s_nop 0
	global_load_dword v31, v[32:33], off offset:1024
	global_load_dword v30, v[32:33], off offset:2048
	global_load_dword v29, v[32:33], off offset:3072
	global_load_dword v34, v[36:37], off
	s_nop 0
	global_load_dword v33, v[36:37], off offset:1024
	global_load_dword v32, v[36:37], off offset:2048
	s_waitcnt vmcnt(36)
	ds_write_b128 v124, v[92:95]
	s_waitcnt vmcnt(35)
	ds_write_b128 v124, v[96:99] offset:8192
	s_waitcnt vmcnt(34)
	ds_write_b128 v124, v[100:103] offset:16384
	s_waitcnt vmcnt(33)
	ds_write_b128 v124, v[104:107] offset:24576
	s_waitcnt vmcnt(32)
	ds_write_b128 v124, v[108:111] offset:32768
	s_waitcnt vmcnt(31)
	s_and_saveexec_b64 s[14:15], s[12:13]
	ds_write_b128 v124, v[112:115] offset:40960
	s_or_b64 exec, exec, s[14:15]
	v_lshlrev_b32_e32 v126, 4, v8
	v_and_b32_e32 v126, 0x3f0, v126
	global_load_dwordx4 v[116:119], v126, s[4:5]
	global_load_dwordx4 v[120:123], v126, s[6:7]
	s_waitcnt lgkmcnt(0)
	s_barrier
	v_ashrrev_i32_e32 v27, 3, v8
	v_lshlrev_b32_sdwa v36, v229, v8 dst_sel:DWORD dst_unused:UNUSED_PAD src0_sel:DWORD src1_sel:BYTE_0
	v_and_b32_e32 v61, 0xffffffe0, v27
	v_add_u32_e32 v62, 0, v36
	v_lshl_add_u32 v78, v61, 9, v62
	v_or_b32_e32 v43, 1, v61
	ds_read_u16 v37, v78
	v_lshl_add_u32 v35, v43, 9, v62
	ds_read_u16 v38, v35
	v_or_b32_e32 v48, 3, v61
	v_or_b32_e32 v72, 6, v61
	v_or_b32_e32 v44, 2, v61
	s_waitcnt lgkmcnt(1)
	v_lshlrev_b32_e32 v45, 16, v37
	v_lshl_add_u32 v37, v48, 9, v62
	v_or_b32_e32 v49, 4, v61
	v_lshl_add_u32 v40, v72, 9, v62
	v_or_b32_e32 v73, 7, v61
	ds_read_u16 v37, v37
	ds_read_u16 v40, v40
	v_lshl_add_u32 v35, v44, 9, v62
	s_waitcnt lgkmcnt(2)
	v_lshlrev_b32_e32 v46, 16, v38
	v_lshl_add_u32 v38, v49, 9, v62
	v_lshl_add_u32 v41, v73, 9, v62
	ds_read_u16 v39, v35
	ds_read_u16 v38, v38
	ds_read_u16 v41, v41
	global_load_dword v35, v152, s[2:3]
	v_or_b32_e32 v50, 5, v61
	s_waitcnt lgkmcnt(2)
	v_lshlrev_b32_e32 v47, 16, v39
	v_lshl_add_u32 v39, v50, 9, v62
	ds_read_u16 v39, v39
	v_or_b32_e32 v60, 8, v61
	v_lshlrev_b32_e32 v74, 16, v37
	v_lshl_add_u32 v37, v60, 9, v62
	s_waitcnt lgkmcnt(2)
	v_lshlrev_b32_e32 v75, 16, v38
	s_waitcnt lgkmcnt(0)
	v_lshlrev_b32_e32 v76, 16, v39
	v_lshlrev_b32_e32 v77, 16, v40
	v_lshlrev_b32_e32 v79, 16, v41
	ds_read_u16 v37, v37
	ds_read_u16 v38, v78 offset:4608
	ds_read_u16 v39, v78 offset:5120
	ds_read_u16 v40, v78 offset:5632
	ds_read_u16 v41, v78 offset:6144
	v_or_b32_e32 v70, 16, v61
	s_waitcnt lgkmcnt(4)
	v_lshlrev_b32_e32 v80, 16, v37
	s_waitcnt lgkmcnt(3)
	v_lshlrev_b32_e32 v81, 16, v38
	s_waitcnt lgkmcnt(1)
	v_lshlrev_b32_e32 v83, 16, v40
	v_lshl_add_u32 v40, v70, 9, v62
	v_lshlrev_b32_e32 v82, 16, v39
	s_waitcnt lgkmcnt(0)
	v_lshlrev_b32_e32 v84, 16, v41
	ds_read_u16 v37, v78 offset:6656
	ds_read_u16 v38, v78 offset:7168
	ds_read_u16 v39, v78 offset:7680
	ds_read_u16 v40, v40
	ds_read_u16 v41, v78 offset:8704
	v_or_b32_e32 v51, 24, v61
	s_waitcnt lgkmcnt(4)
	v_lshlrev_b32_e32 v85, 16, v37
	s_waitcnt lgkmcnt(3)
	v_lshlrev_b32_e32 v86, 16, v38
	s_waitcnt lgkmcnt(2)
	v_lshlrev_b32_e32 v87, 16, v39
	s_waitcnt lgkmcnt(1)
	v_lshlrev_b32_e32 v71, 16, v40
	s_waitcnt lgkmcnt(0)
	v_lshlrev_b32_e32 v53, 16, v41
	ds_read_u16 v37, v78 offset:9216
	ds_read_u16 v38, v78 offset:9728
	ds_read_u16 v39, v78 offset:10240
	ds_read_u16 v40, v78 offset:10752
	ds_read_u16 v41, v78 offset:11264
	s_waitcnt lgkmcnt(4)
	v_lshlrev_b32_e32 v54, 16, v37
	s_waitcnt lgkmcnt(3)
	v_lshlrev_b32_e32 v55, 16, v38
	v_lshl_add_u32 v38, v51, 9, v62
	s_waitcnt lgkmcnt(2)
	v_lshlrev_b32_e32 v56, 16, v39
	s_waitcnt lgkmcnt(1)
	v_lshlrev_b32_e32 v57, 16, v40
	s_waitcnt lgkmcnt(0)
	v_lshlrev_b32_e32 v58, 16, v41
	ds_read_u16 v37, v78 offset:11776
	ds_read_u16 v38, v38
	ds_read_u16 v39, v78 offset:12800
	ds_read_u16 v40, v78 offset:13312
	ds_read_u16 v41, v78 offset:13824
	v_add_u32_e32 v36, v62, v36
	s_waitcnt lgkmcnt(3)
	v_lshlrev_b32_e32 v52, 16, v38
	s_waitcnt lgkmcnt(2)
	v_lshlrev_b32_e32 v63, 16, v39
	s_waitcnt lgkmcnt(1)
	v_lshlrev_b32_e32 v64, 16, v40
	v_mov_b32_e32 v40, 0x3e00
	v_lshl_or_b32 v40, v27, 9, v40
	v_lshlrev_b32_e32 v59, 16, v37
	ds_read_u16 v37, v78 offset:14336
	ds_read_u16 v38, v78 offset:14848
	ds_read_u16 v39, v78 offset:15360
	v_add_u32_e32 v40, v62, v40
	s_waitcnt lgkmcnt(3)
	v_lshlrev_b32_e32 v65, 16, v41
	ds_read_u16 v40, v40
	ds_read_u16 v41, v78 offset:16384
	s_waitcnt lgkmcnt(3)
	v_lshlrev_b32_e32 v67, 16, v38
	s_waitcnt lgkmcnt(2)
	v_lshlrev_b32_e32 v68, 16, v39
	v_lshlrev_b32_e32 v66, 16, v37
	s_waitcnt lgkmcnt(1)
	v_lshlrev_b32_e32 v69, 16, v40
	ds_read_u16 v38, v78 offset:16896
	ds_read_u16 v39, v78 offset:17408
	ds_read_u16 v40, v78 offset:17920
	ds_read_u16 v88, v78 offset:18432
	ds_read_u16 v89, v78 offset:18944
	s_waitcnt lgkmcnt(5)
	v_lshlrev_b32_e32 v37, 16, v41
	s_waitcnt lgkmcnt(3)
	v_lshlrev_b32_e32 v41, 16, v39
	v_lshl_add_u32 v43, v43, 10, v36
	s_waitcnt lgkmcnt(1)
	v_lshlrev_b32_e32 v39, 16, v88
	v_lshl_add_u32 v88, v61, 10, v36
	v_lshl_add_u32 v44, v44, 10, v36
	v_lshlrev_b32_e32 v42, 16, v38
	v_lshlrev_b32_e32 v40, 16, v40
	s_waitcnt lgkmcnt(0)
	v_lshlrev_b32_e32 v38, 16, v89
	v_lshl_add_u32 v60, v60, 10, v36
	v_lshl_add_u32 v70, v70, 10, v36
	v_lshl_add_u32 v51, v51, 10, v36
	s_add_u32 s8, s19, s8
	s_addc_u32 s9, 0, s9
	s_mov_b32 s10, 0
	s_waitcnt vmcnt(0)
	v_fma_f32 v45, v3, v45, v35
	v_fmac_f32_e32 v45, v2, v46
	v_fmac_f32_e32 v45, v1, v47
	v_fmac_f32_e32 v45, v0, v74
	v_fmac_f32_e32 v45, v7, v75
	v_fmac_f32_e32 v45, v6, v76
	v_fmac_f32_e32 v45, v5, v77
	v_fmac_f32_e32 v45, v4, v79
	v_fmac_f32_e32 v45, v18, v80
	v_fmac_f32_e32 v45, v17, v81
	v_fmac_f32_e32 v45, v16, v82
	v_fmac_f32_e32 v45, v15, v83
	v_fmac_f32_e32 v45, v14, v84
	v_fmac_f32_e32 v45, v13, v85
	v_fmac_f32_e32 v45, v12, v86
	v_fmac_f32_e32 v45, v9, v87
	v_fmac_f32_e32 v45, v19, v71
	v_fmac_f32_e32 v45, v22, v53
	v_fmac_f32_e32 v45, v21, v54
	v_fmac_f32_e32 v45, v20, v55
	v_fmac_f32_e32 v45, v26, v56
	v_fmac_f32_e32 v45, v25, v57
	v_fmac_f32_e32 v45, v24, v58
	v_fmac_f32_e32 v45, v23, v59
	v_fmac_f32_e32 v45, v28, v52
	v_fmac_f32_e32 v45, v31, v63
	v_fmac_f32_e32 v45, v30, v64
	v_fmac_f32_e32 v45, v29, v65
	v_fmac_f32_e32 v45, v34, v66
	v_fmac_f32_e32 v45, v33, v67
	v_fmac_f32_e32 v45, v32, v68
	ds_write_b32 v88, v45 offset:49152
	v_fma_f32 v45, v3, v46, v35
	v_fmac_f32_e32 v45, v2, v47
	v_fmac_f32_e32 v45, v1, v74
	v_fmac_f32_e32 v45, v0, v75
	v_fmac_f32_e32 v45, v7, v76
	v_fmac_f32_e32 v45, v6, v77
	v_fmac_f32_e32 v45, v5, v79
	v_fmac_f32_e32 v45, v4, v80
	v_fmac_f32_e32 v45, v18, v81
	v_fmac_f32_e32 v45, v17, v82
	v_fmac_f32_e32 v45, v16, v83
	v_fmac_f32_e32 v45, v15, v84
	v_fmac_f32_e32 v45, v14, v85
	v_fmac_f32_e32 v45, v13, v86
	v_fmac_f32_e32 v45, v12, v87
	v_fmac_f32_e32 v45, v9, v71
	v_fmac_f32_e32 v45, v19, v53
	v_fmac_f32_e32 v45, v22, v54
	v_fmac_f32_e32 v45, v21, v55
	v_fmac_f32_e32 v45, v20, v56
	v_fmac_f32_e32 v45, v26, v57
	v_fmac_f32_e32 v45, v25, v58
	v_fmac_f32_e32 v45, v24, v59
	v_fmac_f32_e32 v45, v23, v52
	v_fmac_f32_e32 v45, v28, v63
	v_fmac_f32_e32 v45, v31, v64
	v_fmac_f32_e32 v45, v30, v65
	v_fmac_f32_e32 v45, v29, v66
	v_fmac_f32_e32 v45, v34, v67
	v_fmac_f32_e32 v45, v33, v68
	v_fmac_f32_e32 v45, v32, v69
	ds_write_b32 v43, v45 offset:49152
	v_fma_f32 v43, v3, v47, v35
	v_fmac_f32_e32 v43, v2, v74
	v_fmac_f32_e32 v43, v1, v75
	v_fmac_f32_e32 v43, v0, v76
	v_fmac_f32_e32 v43, v7, v77
	v_fmac_f32_e32 v43, v6, v79
	v_fmac_f32_e32 v43, v5, v80
	v_fmac_f32_e32 v43, v4, v81
	v_fmac_f32_e32 v43, v18, v82
	v_fmac_f32_e32 v43, v17, v83
	v_fmac_f32_e32 v43, v16, v84
	v_fmac_f32_e32 v43, v15, v85
	v_fmac_f32_e32 v43, v14, v86
	v_fmac_f32_e32 v43, v13, v87
	v_fmac_f32_e32 v43, v12, v71
	v_fmac_f32_e32 v43, v9, v53
	v_fmac_f32_e32 v43, v19, v54
	v_fmac_f32_e32 v43, v22, v55
	v_fmac_f32_e32 v43, v21, v56
	v_fmac_f32_e32 v43, v20, v57
	v_fmac_f32_e32 v43, v26, v58
	v_fmac_f32_e32 v43, v25, v59
	v_fmac_f32_e32 v43, v24, v52
	v_fmac_f32_e32 v43, v23, v63
	v_fmac_f32_e32 v43, v28, v64
	v_fmac_f32_e32 v43, v31, v65
	v_fmac_f32_e32 v43, v30, v66
	v_fmac_f32_e32 v43, v29, v67
	v_fmac_f32_e32 v43, v34, v68
	v_fmac_f32_e32 v43, v33, v69
	v_fmac_f32_e32 v43, v32, v37
	ds_write_b32 v44, v43 offset:49152
	v_fma_f32 v43, v3, v74, v35
	v_fmac_f32_e32 v43, v2, v75
	v_fmac_f32_e32 v43, v1, v76
	v_fmac_f32_e32 v43, v0, v77
	v_fmac_f32_e32 v43, v7, v79
	v_fmac_f32_e32 v43, v6, v80
	v_fmac_f32_e32 v43, v5, v81
	v_fmac_f32_e32 v43, v4, v82
	v_fmac_f32_e32 v43, v18, v83
	v_fmac_f32_e32 v43, v17, v84
	v_fmac_f32_e32 v43, v16, v85
	v_fmac_f32_e32 v43, v15, v86
	v_fmac_f32_e32 v43, v14, v87
	v_fmac_f32_e32 v43, v13, v71
	v_fmac_f32_e32 v43, v12, v53
	v_fmac_f32_e32 v43, v9, v54
	v_fmac_f32_e32 v43, v19, v55
	v_fmac_f32_e32 v43, v22, v56
	v_fmac_f32_e32 v43, v21, v57
	v_fmac_f32_e32 v43, v20, v58
	v_fmac_f32_e32 v43, v26, v59
	v_fmac_f32_e32 v43, v25, v52
	v_fmac_f32_e32 v43, v24, v63
	v_fmac_f32_e32 v43, v23, v64
	v_fmac_f32_e32 v43, v28, v65
	v_fmac_f32_e32 v43, v31, v66
	v_fmac_f32_e32 v43, v30, v67
	v_fmac_f32_e32 v43, v29, v68
	v_fmac_f32_e32 v43, v34, v69
	v_fmac_f32_e32 v43, v33, v37
	v_fmac_f32_e32 v43, v32, v42
	v_lshl_add_u32 v44, v48, 10, v36
	ds_write_b32 v44, v43 offset:49152
	v_fma_f32 v43, v3, v75, v35
	v_fmac_f32_e32 v43, v2, v76
	v_fmac_f32_e32 v43, v1, v77
	v_fmac_f32_e32 v43, v0, v79
	v_fmac_f32_e32 v43, v7, v80
	v_fmac_f32_e32 v43, v6, v81
	v_fmac_f32_e32 v43, v5, v82
	v_fmac_f32_e32 v43, v4, v83
	v_fmac_f32_e32 v43, v18, v84
	v_fmac_f32_e32 v43, v17, v85
	v_fmac_f32_e32 v43, v16, v86
	v_fmac_f32_e32 v43, v15, v87
	v_fmac_f32_e32 v43, v14, v71
	v_fmac_f32_e32 v43, v13, v53
	v_fmac_f32_e32 v43, v12, v54
	v_fmac_f32_e32 v43, v9, v55
	v_fmac_f32_e32 v43, v19, v56
	v_fmac_f32_e32 v43, v22, v57
	v_fmac_f32_e32 v43, v21, v58
	v_fmac_f32_e32 v43, v20, v59
	v_fmac_f32_e32 v43, v26, v52
	v_fmac_f32_e32 v43, v25, v63
	v_fmac_f32_e32 v43, v24, v64
	v_fmac_f32_e32 v43, v23, v65
	v_fmac_f32_e32 v43, v28, v66
	v_fmac_f32_e32 v43, v31, v67
	v_fmac_f32_e32 v43, v30, v68
	v_fmac_f32_e32 v43, v29, v69
	v_fmac_f32_e32 v43, v34, v37
	v_fmac_f32_e32 v43, v33, v42
	v_fmac_f32_e32 v43, v32, v41
	v_lshl_add_u32 v44, v49, 10, v36
	ds_write_b32 v44, v43 offset:49152
	v_fma_f32 v43, v3, v76, v35
	v_fmac_f32_e32 v43, v2, v77
	v_fmac_f32_e32 v43, v1, v79
	v_fmac_f32_e32 v43, v0, v80
	v_fmac_f32_e32 v43, v7, v81
	v_fmac_f32_e32 v43, v6, v82
	v_fmac_f32_e32 v43, v5, v83
	v_fmac_f32_e32 v43, v4, v84
	v_fmac_f32_e32 v43, v18, v85
	v_fmac_f32_e32 v43, v17, v86
	v_fmac_f32_e32 v43, v16, v87
	v_fmac_f32_e32 v43, v15, v71
	v_fmac_f32_e32 v43, v14, v53
	v_fmac_f32_e32 v43, v13, v54
	v_fmac_f32_e32 v43, v12, v55
	v_fmac_f32_e32 v43, v9, v56
	v_fmac_f32_e32 v43, v19, v57
	v_fmac_f32_e32 v43, v22, v58
	v_fmac_f32_e32 v43, v21, v59
	v_fmac_f32_e32 v43, v20, v52
	v_fmac_f32_e32 v43, v26, v63
	v_fmac_f32_e32 v43, v25, v64
	v_fmac_f32_e32 v43, v24, v65
	v_fmac_f32_e32 v43, v23, v66
	v_fmac_f32_e32 v43, v28, v67
	v_fmac_f32_e32 v43, v31, v68
	v_fmac_f32_e32 v43, v30, v69
	v_fmac_f32_e32 v43, v29, v37
	v_fmac_f32_e32 v43, v34, v42
	v_fmac_f32_e32 v43, v33, v41
	v_fmac_f32_e32 v43, v32, v40
	v_lshl_add_u32 v44, v50, 10, v36
	ds_write_b32 v44, v43 offset:49152
	v_fma_f32 v43, v3, v77, v35
	v_fmac_f32_e32 v43, v2, v79
	v_fmac_f32_e32 v43, v1, v80
	v_fmac_f32_e32 v43, v0, v81
	v_fmac_f32_e32 v43, v7, v82
	v_fmac_f32_e32 v43, v6, v83
	v_fmac_f32_e32 v43, v5, v84
	v_fmac_f32_e32 v43, v4, v85
	v_fmac_f32_e32 v43, v18, v86
	v_fmac_f32_e32 v43, v17, v87
	v_fmac_f32_e32 v43, v16, v71
	v_fmac_f32_e32 v43, v15, v53
	v_fmac_f32_e32 v43, v14, v54
	v_fmac_f32_e32 v43, v13, v55
	v_fmac_f32_e32 v43, v12, v56
	v_fmac_f32_e32 v43, v9, v57
	v_fmac_f32_e32 v43, v19, v58
	v_fmac_f32_e32 v43, v22, v59
	v_fmac_f32_e32 v43, v21, v52
	v_fmac_f32_e32 v43, v20, v63
	v_fmac_f32_e32 v43, v26, v64
	v_fmac_f32_e32 v43, v25, v65
	v_fmac_f32_e32 v43, v24, v66
	v_fmac_f32_e32 v43, v23, v67
	v_fmac_f32_e32 v43, v28, v68
	v_fmac_f32_e32 v43, v31, v69
	v_fmac_f32_e32 v43, v30, v37
	v_fmac_f32_e32 v43, v29, v42
	v_fmac_f32_e32 v43, v34, v41
	v_fmac_f32_e32 v43, v33, v40
	v_fmac_f32_e32 v43, v32, v39
	v_lshl_add_u32 v44, v72, 10, v36
	ds_write_b32 v44, v43 offset:49152
	v_fma_f32 v43, v3, v79, v35
	v_fmac_f32_e32 v43, v2, v80
	v_fmac_f32_e32 v43, v1, v81
	v_fmac_f32_e32 v43, v0, v82
	v_fmac_f32_e32 v43, v7, v83
	v_fmac_f32_e32 v43, v6, v84
	v_fmac_f32_e32 v43, v5, v85
	v_fmac_f32_e32 v43, v4, v86
	v_fmac_f32_e32 v43, v18, v87
	v_fmac_f32_e32 v43, v17, v71
	v_fmac_f32_e32 v43, v16, v53
	v_fmac_f32_e32 v43, v15, v54
	v_fmac_f32_e32 v43, v14, v55
	v_fmac_f32_e32 v43, v13, v56
	v_fmac_f32_e32 v43, v12, v57
	v_fmac_f32_e32 v43, v9, v58
	v_fmac_f32_e32 v43, v19, v59
	v_fmac_f32_e32 v43, v22, v52
	v_fmac_f32_e32 v43, v21, v63
	v_fmac_f32_e32 v43, v20, v64
	v_fmac_f32_e32 v43, v26, v65
	v_fmac_f32_e32 v43, v25, v66
	v_fmac_f32_e32 v43, v24, v67
	v_fmac_f32_e32 v43, v23, v68
	v_fmac_f32_e32 v43, v28, v69
	v_fmac_f32_e32 v43, v31, v37
	v_or_b32_e32 v74, 9, v61
	v_fmac_f32_e32 v43, v30, v42
	v_lshl_add_u32 v44, v74, 9, v62
	v_or_b32_e32 v75, 10, v61
	v_fmac_f32_e32 v43, v29, v41
	ds_read_u16 v44, v44
	v_lshl_add_u32 v45, v75, 9, v62
	v_fmac_f32_e32 v43, v34, v40
	ds_read_u16 v45, v45
	v_fmac_f32_e32 v43, v33, v39
	v_fmac_f32_e32 v43, v32, v38
	v_lshl_add_u32 v46, v73, 10, v36
	v_or_b32_e32 v77, 11, v61
	v_or_b32_e32 v82, 14, v61
	ds_write_b32 v46, v43 offset:49152
	v_lshl_add_u32 v43, v77, 9, v62
	v_or_b32_e32 v79, 12, v61
	v_lshl_add_u32 v46, v82, 9, v62
	v_or_b32_e32 v81, 13, v61
	ds_read_u16 v46, v46
	ds_read_u16 v43, v43
	s_waitcnt lgkmcnt(4)
	v_lshlrev_b32_e32 v73, 16, v44
	v_lshl_add_u32 v44, v79, 9, v62
	s_waitcnt lgkmcnt(3)
	v_lshlrev_b32_e32 v76, 16, v45
	ds_read_u16 v44, v44
	v_lshl_add_u32 v45, v81, 9, v62
	ds_read_u16 v45, v45
	v_or_b32_e32 v83, 15, v61
	v_lshl_add_u32 v47, v83, 9, v62
	v_fma_f32 v80, v3, v80, v35
	ds_read_u16 v47, v47
	v_fmac_f32_e32 v80, v2, v73
	s_waitcnt lgkmcnt(3)
	v_lshlrev_b32_e32 v84, 16, v43
	v_fmac_f32_e32 v80, v1, v76
	s_waitcnt lgkmcnt(2)
	v_lshlrev_b32_e32 v85, 16, v44
	v_fmac_f32_e32 v80, v0, v84
	s_waitcnt lgkmcnt(1)
	v_lshlrev_b32_e32 v86, 16, v45
	v_fmac_f32_e32 v80, v7, v85
	v_lshlrev_b32_e32 v87, 16, v46
	v_fmac_f32_e32 v80, v6, v86
	s_waitcnt lgkmcnt(0)
	v_lshlrev_b32_e32 v88, 16, v47
	ds_read_u16 v43, v78 offset:8192
	ds_read_u16 v44, v78 offset:12288
	ds_read_u16 v45, v78 offset:19456
	ds_read_u16 v46, v78 offset:19968
	ds_read_u16 v48, v78 offset:20480
	v_fmac_f32_e32 v80, v5, v87
	s_waitcnt lgkmcnt(4)
	v_lshlrev_b32_e32 v89, 16, v43
	v_fmac_f32_e32 v80, v4, v88
	v_fmac_f32_e32 v80, v18, v89
	v_fmac_f32_e32 v80, v17, v53
	v_fmac_f32_e32 v80, v16, v54
	v_fmac_f32_e32 v80, v15, v55
	v_fmac_f32_e32 v80, v14, v56
	v_fmac_f32_e32 v80, v13, v57
	v_fmac_f32_e32 v80, v12, v58
	s_waitcnt lgkmcnt(3)
	v_lshlrev_b32_e32 v72, 16, v44
	v_fmac_f32_e32 v80, v9, v59
	v_fmac_f32_e32 v80, v19, v72
	v_fmac_f32_e32 v80, v22, v63
	v_fmac_f32_e32 v80, v21, v64
	v_fmac_f32_e32 v80, v20, v65
	v_fmac_f32_e32 v80, v26, v66
	v_fmac_f32_e32 v80, v25, v67
	v_fmac_f32_e32 v80, v24, v68
	v_fmac_f32_e32 v80, v23, v69
	v_fmac_f32_e32 v80, v28, v37
	v_fmac_f32_e32 v80, v31, v42
	v_fmac_f32_e32 v80, v30, v41
	v_fmac_f32_e32 v80, v29, v40
	v_fmac_f32_e32 v80, v34, v39
	s_waitcnt lgkmcnt(2)
	v_lshlrev_b32_e32 v47, 16, v45
	v_fmac_f32_e32 v80, v33, v38
	v_fmac_f32_e32 v80, v32, v47
	s_waitcnt lgkmcnt(1)
	v_lshlrev_b32_e32 v45, 16, v46
	s_waitcnt lgkmcnt(0)
	v_lshlrev_b32_e32 v43, 16, v48
	ds_read_u16 v44, v78 offset:20992
	ds_read_u16 v46, v78 offset:21504
	ds_read_u16 v48, v78 offset:22016
	ds_read_u16 v90, v78 offset:22528
	ds_read_u16 v91, v78 offset:23040
	ds_write_b32 v60, v80 offset:49152
	v_fma_f32 v60, v3, v73, v35
	v_fmac_f32_e32 v60, v2, v76
	v_fmac_f32_e32 v60, v1, v84
	v_fmac_f32_e32 v60, v0, v85
	v_fmac_f32_e32 v60, v7, v86
	v_fmac_f32_e32 v60, v6, v87
	v_fmac_f32_e32 v60, v5, v88
	v_fmac_f32_e32 v60, v4, v89
	v_fmac_f32_e32 v60, v18, v53
	v_fmac_f32_e32 v60, v17, v54
	v_fmac_f32_e32 v60, v16, v55
	v_fmac_f32_e32 v60, v15, v56
	v_fmac_f32_e32 v60, v14, v57
	v_fmac_f32_e32 v60, v13, v58
	v_fmac_f32_e32 v60, v12, v59
	v_fmac_f32_e32 v60, v9, v72
	v_fmac_f32_e32 v60, v19, v63
	v_fmac_f32_e32 v60, v22, v64
	v_fmac_f32_e32 v60, v21, v65
	v_fmac_f32_e32 v60, v20, v66
	v_fmac_f32_e32 v60, v26, v67
	v_fmac_f32_e32 v60, v25, v68
	v_fmac_f32_e32 v60, v24, v69
	v_fmac_f32_e32 v60, v23, v37
	v_fmac_f32_e32 v60, v28, v42
	v_fmac_f32_e32 v60, v31, v41
	v_fmac_f32_e32 v60, v30, v40
	v_fmac_f32_e32 v60, v29, v39
	v_fmac_f32_e32 v60, v34, v38
	v_fmac_f32_e32 v60, v33, v47
	v_fmac_f32_e32 v60, v32, v45
	v_lshl_add_u32 v73, v74, 10, v36
	ds_write_b32 v73, v60 offset:49152
	v_fma_f32 v60, v3, v76, v35
	v_fmac_f32_e32 v60, v2, v84
	v_fmac_f32_e32 v60, v1, v85
	v_fmac_f32_e32 v60, v0, v86
	v_fmac_f32_e32 v60, v7, v87
	v_fmac_f32_e32 v60, v6, v88
	v_fmac_f32_e32 v60, v5, v89
	v_fmac_f32_e32 v60, v4, v53
	v_fmac_f32_e32 v60, v18, v54
	v_fmac_f32_e32 v60, v17, v55
	v_fmac_f32_e32 v60, v16, v56
	v_fmac_f32_e32 v60, v15, v57
	v_fmac_f32_e32 v60, v14, v58
	v_fmac_f32_e32 v60, v13, v59
	v_fmac_f32_e32 v60, v12, v72
	v_fmac_f32_e32 v60, v9, v63
	v_fmac_f32_e32 v60, v19, v64
	v_fmac_f32_e32 v60, v22, v65
	v_fmac_f32_e32 v60, v21, v66
	v_fmac_f32_e32 v60, v20, v67
	v_fmac_f32_e32 v60, v26, v68
	v_fmac_f32_e32 v60, v25, v69
	v_fmac_f32_e32 v60, v24, v37
	v_fmac_f32_e32 v60, v23, v42
	v_fmac_f32_e32 v60, v28, v41
	v_fmac_f32_e32 v60, v31, v40
	v_fmac_f32_e32 v60, v30, v39
	v_fmac_f32_e32 v60, v29, v38
	v_fmac_f32_e32 v60, v34, v47
	v_fmac_f32_e32 v60, v33, v45
	v_fmac_f32_e32 v60, v32, v43
	v_lshl_add_u32 v73, v75, 10, v36
	ds_write_b32 v73, v60 offset:49152
	v_fma_f32 v60, v3, v84, v35
	v_fmac_f32_e32 v60, v2, v85
	v_fmac_f32_e32 v60, v1, v86
	v_fmac_f32_e32 v60, v0, v87
	v_fmac_f32_e32 v60, v7, v88
	v_fmac_f32_e32 v60, v6, v89
	v_fmac_f32_e32 v60, v5, v53
	v_fmac_f32_e32 v60, v4, v54
	v_fmac_f32_e32 v60, v18, v55
	v_fmac_f32_e32 v60, v17, v56
	v_fmac_f32_e32 v60, v16, v57
	v_fmac_f32_e32 v60, v15, v58
	v_fmac_f32_e32 v60, v14, v59
	v_fmac_f32_e32 v60, v13, v72
	v_fmac_f32_e32 v60, v12, v63
	v_fmac_f32_e32 v60, v9, v64
	v_fmac_f32_e32 v60, v19, v65
	v_fmac_f32_e32 v60, v22, v66
	v_fmac_f32_e32 v60, v21, v67
	v_fmac_f32_e32 v60, v20, v68
	v_fmac_f32_e32 v60, v26, v69
	v_fmac_f32_e32 v60, v25, v37
	v_fmac_f32_e32 v60, v24, v42
	v_fmac_f32_e32 v60, v23, v41
	v_fmac_f32_e32 v60, v28, v40
	v_fmac_f32_e32 v60, v31, v39
	v_fmac_f32_e32 v60, v30, v38
	v_fmac_f32_e32 v60, v29, v47
	v_fmac_f32_e32 v60, v34, v45
	s_waitcnt lgkmcnt(7)
	v_lshlrev_b32_e32 v50, 16, v44
	v_fmac_f32_e32 v60, v33, v43
	v_fmac_f32_e32 v60, v32, v50
	v_lshl_add_u32 v73, v77, 10, v36
	ds_write_b32 v73, v60 offset:49152
	v_fma_f32 v60, v3, v85, v35
	v_fmac_f32_e32 v60, v2, v86
	v_fmac_f32_e32 v60, v1, v87
	v_fmac_f32_e32 v60, v0, v88
	v_fmac_f32_e32 v60, v7, v89
	v_fmac_f32_e32 v60, v6, v53
	v_fmac_f32_e32 v60, v5, v54
	v_fmac_f32_e32 v60, v4, v55
	v_fmac_f32_e32 v60, v18, v56
	v_fmac_f32_e32 v60, v17, v57
	v_fmac_f32_e32 v60, v16, v58
	v_fmac_f32_e32 v60, v15, v59
	v_fmac_f32_e32 v60, v14, v72
	v_fmac_f32_e32 v60, v13, v63
	v_fmac_f32_e32 v60, v12, v64
	v_fmac_f32_e32 v60, v9, v65
	v_fmac_f32_e32 v60, v19, v66
	v_fmac_f32_e32 v60, v22, v67
	v_fmac_f32_e32 v60, v21, v68
	v_fmac_f32_e32 v60, v20, v69
	v_fmac_f32_e32 v60, v26, v37
	v_fmac_f32_e32 v60, v25, v42
	v_fmac_f32_e32 v60, v24, v41
	v_fmac_f32_e32 v60, v23, v40
	v_fmac_f32_e32 v60, v28, v39
	v_fmac_f32_e32 v60, v31, v38
	v_fmac_f32_e32 v60, v30, v47
	v_fmac_f32_e32 v60, v29, v45
	v_fmac_f32_e32 v60, v34, v43
	s_waitcnt lgkmcnt(7)
	v_lshlrev_b32_e32 v49, 16, v46
	v_fmac_f32_e32 v60, v33, v50
	v_fmac_f32_e32 v60, v32, v49
	v_lshl_add_u32 v73, v79, 10, v36
	ds_write_b32 v73, v60 offset:49152
	v_fma_f32 v60, v3, v86, v35
	v_fmac_f32_e32 v60, v2, v87
	v_fmac_f32_e32 v60, v1, v88
	v_fmac_f32_e32 v60, v0, v89
	v_fmac_f32_e32 v60, v7, v53
	v_fmac_f32_e32 v60, v6, v54
	v_fmac_f32_e32 v60, v5, v55
	v_fmac_f32_e32 v60, v4, v56
	v_fmac_f32_e32 v60, v18, v57
	v_fmac_f32_e32 v60, v17, v58
	v_fmac_f32_e32 v60, v16, v59
	v_fmac_f32_e32 v60, v15, v72
	v_fmac_f32_e32 v60, v14, v63
	v_fmac_f32_e32 v60, v13, v64
	v_fmac_f32_e32 v60, v12, v65
	v_fmac_f32_e32 v60, v9, v66
	v_fmac_f32_e32 v60, v19, v67
	v_fmac_f32_e32 v60, v22, v68
	v_fmac_f32_e32 v60, v21, v69
	v_fmac_f32_e32 v60, v20, v37
	v_fmac_f32_e32 v60, v26, v42
	v_fmac_f32_e32 v60, v25, v41
	v_fmac_f32_e32 v60, v24, v40
	v_fmac_f32_e32 v60, v23, v39
	v_fmac_f32_e32 v60, v28, v38
	v_fmac_f32_e32 v60, v31, v47
	v_fmac_f32_e32 v60, v30, v45
	v_fmac_f32_e32 v60, v29, v43
	v_fmac_f32_e32 v60, v34, v50
	s_waitcnt lgkmcnt(7)
	v_lshlrev_b32_e32 v48, 16, v48
	v_fmac_f32_e32 v60, v33, v49
	v_fmac_f32_e32 v60, v32, v48
	v_lshl_add_u32 v73, v81, 10, v36
	ds_write_b32 v73, v60 offset:49152
	v_fma_f32 v60, v3, v87, v35
	v_fmac_f32_e32 v60, v2, v88
	v_fmac_f32_e32 v60, v1, v89
	v_fmac_f32_e32 v60, v0, v53
	v_fmac_f32_e32 v60, v7, v54
	v_fmac_f32_e32 v60, v6, v55
	v_fmac_f32_e32 v60, v5, v56
	v_fmac_f32_e32 v60, v4, v57
	v_fmac_f32_e32 v60, v18, v58
	v_fmac_f32_e32 v60, v17, v59
	v_fmac_f32_e32 v60, v16, v72
	v_fmac_f32_e32 v60, v15, v63
	v_fmac_f32_e32 v60, v14, v64
	v_fmac_f32_e32 v60, v13, v65
	v_fmac_f32_e32 v60, v12, v66
	v_fmac_f32_e32 v60, v9, v67
	v_fmac_f32_e32 v60, v19, v68
	v_fmac_f32_e32 v60, v22, v69
	v_fmac_f32_e32 v60, v21, v37
	v_fmac_f32_e32 v60, v20, v42
	v_fmac_f32_e32 v60, v26, v41
	v_fmac_f32_e32 v60, v25, v40
	v_fmac_f32_e32 v60, v24, v39
	v_fmac_f32_e32 v60, v23, v38
	v_fmac_f32_e32 v60, v28, v47
	v_fmac_f32_e32 v60, v31, v45
	v_fmac_f32_e32 v60, v30, v43
	v_fmac_f32_e32 v60, v29, v50
	v_fmac_f32_e32 v60, v34, v49
	s_waitcnt lgkmcnt(7)
	v_lshlrev_b32_e32 v46, 16, v90
	v_fmac_f32_e32 v60, v33, v48
	v_fmac_f32_e32 v60, v32, v46
	v_lshl_add_u32 v73, v82, 10, v36
	ds_write_b32 v73, v60 offset:49152
	v_fma_f32 v60, v3, v88, v35
	v_fmac_f32_e32 v60, v2, v89
	v_fmac_f32_e32 v60, v1, v53
	v_fmac_f32_e32 v60, v0, v54
	v_fmac_f32_e32 v60, v7, v55
	v_fmac_f32_e32 v60, v6, v56
	v_fmac_f32_e32 v60, v5, v57
	v_fmac_f32_e32 v60, v4, v58
	v_fmac_f32_e32 v60, v18, v59
	v_fmac_f32_e32 v60, v17, v72
	v_fmac_f32_e32 v60, v16, v63
	v_fmac_f32_e32 v60, v15, v64
	v_fmac_f32_e32 v60, v14, v65
	v_fmac_f32_e32 v60, v13, v66
	v_fmac_f32_e32 v60, v12, v67
	v_fmac_f32_e32 v60, v9, v68
	v_fmac_f32_e32 v60, v19, v69
	v_fmac_f32_e32 v60, v22, v37
	v_fmac_f32_e32 v60, v21, v42
	v_fmac_f32_e32 v60, v20, v41
	v_fmac_f32_e32 v60, v26, v40
	v_fmac_f32_e32 v60, v25, v39
	v_fmac_f32_e32 v60, v24, v38
	v_fmac_f32_e32 v60, v23, v47
	v_fmac_f32_e32 v60, v28, v45
	v_fmac_f32_e32 v60, v31, v43
	v_fmac_f32_e32 v60, v30, v50
	v_fmac_f32_e32 v60, v29, v49
	v_fmac_f32_e32 v60, v34, v48
	s_waitcnt lgkmcnt(7)
	v_lshlrev_b32_e32 v44, 16, v91
	v_fmac_f32_e32 v60, v33, v46
	v_fmac_f32_e32 v60, v32, v44
	v_lshl_add_u32 v53, v83, 10, v36
	v_or_b32_e32 v73, 17, v61
	ds_write_b32 v53, v60 offset:49152
	v_lshl_add_u32 v53, v73, 9, v62
	ds_read_u16 v53, v53
	v_or_b32_e32 v74, 18, v61
	v_lshl_add_u32 v54, v74, 9, v62
	v_or_b32_e32 v75, 19, v61
	ds_read_u16 v54, v54
	v_lshl_add_u32 v55, v75, 9, v62
	v_or_b32_e32 v76, 20, v61
	ds_read_u16 v55, v55
	v_lshl_add_u32 v56, v76, 9, v62
	v_or_b32_e32 v77, 21, v61
	ds_read_u16 v56, v56
	v_lshl_add_u32 v57, v77, 9, v62
	v_or_b32_e32 v84, 22, v61
	ds_read_u16 v57, v57
	s_waitcnt lgkmcnt(4)
	v_lshlrev_b32_e32 v79, 16, v53
	v_lshl_add_u32 v53, v84, 9, v62
	ds_read_u16 v53, v53
	v_fma_f32 v71, v3, v71, v35
	s_waitcnt lgkmcnt(4)
	v_lshlrev_b32_e32 v80, 16, v54
	v_fmac_f32_e32 v71, v2, v79
	s_waitcnt lgkmcnt(3)
	v_lshlrev_b32_e32 v81, 16, v55
	v_or_b32_e32 v85, 23, v61
	v_fmac_f32_e32 v71, v1, v80
	s_waitcnt lgkmcnt(2)
	v_lshlrev_b32_e32 v82, 16, v56
	v_lshl_add_u32 v54, v85, 9, v62
	v_fmac_f32_e32 v71, v0, v81
	s_waitcnt lgkmcnt(1)
	v_lshlrev_b32_e32 v83, 16, v57
	ds_read_u16 v54, v54
	ds_read_u16 v55, v78 offset:23552
	ds_read_u16 v56, v78 offset:24064
	ds_read_u16 v58, v78 offset:24576
	v_fmac_f32_e32 v71, v7, v82
	s_waitcnt lgkmcnt(4)
	v_lshlrev_b32_e32 v86, 16, v53
	v_fmac_f32_e32 v71, v6, v83
	s_waitcnt lgkmcnt(3)
	v_lshlrev_b32_e32 v87, 16, v54
	v_fmac_f32_e32 v71, v5, v86
	v_fmac_f32_e32 v71, v4, v87
	v_fmac_f32_e32 v71, v18, v72
	v_fmac_f32_e32 v71, v17, v63
	v_fmac_f32_e32 v71, v16, v64
	v_fmac_f32_e32 v71, v15, v65
	v_fmac_f32_e32 v71, v14, v66
	v_fmac_f32_e32 v71, v13, v67
	v_fmac_f32_e32 v71, v12, v68
	v_fmac_f32_e32 v71, v9, v69
	v_fmac_f32_e32 v71, v19, v37
	v_fmac_f32_e32 v71, v22, v42
	v_fmac_f32_e32 v71, v21, v41
	v_fmac_f32_e32 v71, v20, v40
	v_fmac_f32_e32 v71, v26, v39
	v_fmac_f32_e32 v71, v25, v38
	v_fmac_f32_e32 v71, v24, v47
	v_fmac_f32_e32 v71, v23, v45
	v_fmac_f32_e32 v71, v28, v43
	v_fmac_f32_e32 v71, v31, v50
	v_fmac_f32_e32 v71, v30, v49
	v_fmac_f32_e32 v71, v29, v48
	v_fmac_f32_e32 v71, v34, v46
	s_waitcnt lgkmcnt(2)
	v_lshlrev_b32_e32 v57, 16, v55
	v_fmac_f32_e32 v71, v33, v44
	v_fmac_f32_e32 v71, v32, v57
	s_waitcnt lgkmcnt(1)
	v_lshlrev_b32_e32 v55, 16, v56
	s_waitcnt lgkmcnt(0)
	v_lshlrev_b32_e32 v53, 16, v58
	ds_read_u16 v54, v78 offset:25088
	ds_read_u16 v56, v78 offset:25600
	ds_read_u16 v58, v78 offset:26112
	ds_read_u16 v88, v78 offset:26624
	ds_read_u16 v89, v78 offset:27136
	ds_write_b32 v70, v71 offset:49152
	v_fma_f32 v70, v3, v79, v35
	v_fmac_f32_e32 v70, v2, v80
	v_fmac_f32_e32 v70, v1, v81
	v_fmac_f32_e32 v70, v0, v82
	v_fmac_f32_e32 v70, v7, v83
	v_fmac_f32_e32 v70, v6, v86
	v_fmac_f32_e32 v70, v5, v87
	v_fmac_f32_e32 v70, v4, v72
	v_fmac_f32_e32 v70, v18, v63
	v_fmac_f32_e32 v70, v17, v64
	v_fmac_f32_e32 v70, v16, v65
	v_fmac_f32_e32 v70, v15, v66
	v_fmac_f32_e32 v70, v14, v67
	v_fmac_f32_e32 v70, v13, v68
	v_fmac_f32_e32 v70, v12, v69
	v_fmac_f32_e32 v70, v9, v37
	v_fmac_f32_e32 v70, v19, v42
	v_fmac_f32_e32 v70, v22, v41
	v_fmac_f32_e32 v70, v21, v40
	v_fmac_f32_e32 v70, v20, v39
	v_fmac_f32_e32 v70, v26, v38
	v_fmac_f32_e32 v70, v25, v47
	v_fmac_f32_e32 v70, v24, v45
	v_fmac_f32_e32 v70, v23, v43
	v_fmac_f32_e32 v70, v28, v50
	v_fmac_f32_e32 v70, v31, v49
	v_fmac_f32_e32 v70, v30, v48
	v_fmac_f32_e32 v70, v29, v46
	v_fmac_f32_e32 v70, v34, v44
	v_fmac_f32_e32 v70, v33, v57
	v_fmac_f32_e32 v70, v32, v55
	v_lshl_add_u32 v71, v73, 10, v36
	ds_write_b32 v71, v70 offset:49152
	v_fma_f32 v70, v3, v80, v35
	v_fmac_f32_e32 v70, v2, v81
	v_fmac_f32_e32 v70, v1, v82
	v_fmac_f32_e32 v70, v0, v83
	v_fmac_f32_e32 v70, v7, v86
	v_fmac_f32_e32 v70, v6, v87
	v_fmac_f32_e32 v70, v5, v72
	v_fmac_f32_e32 v70, v4, v63
	v_fmac_f32_e32 v70, v18, v64
	v_fmac_f32_e32 v70, v17, v65
	v_fmac_f32_e32 v70, v16, v66
	v_fmac_f32_e32 v70, v15, v67
	v_fmac_f32_e32 v70, v14, v68
	v_fmac_f32_e32 v70, v13, v69
	v_fmac_f32_e32 v70, v12, v37
	v_fmac_f32_e32 v70, v9, v42
	v_fmac_f32_e32 v70, v19, v41
	v_fmac_f32_e32 v70, v22, v40
	v_fmac_f32_e32 v70, v21, v39
	v_fmac_f32_e32 v70, v20, v38
	v_fmac_f32_e32 v70, v26, v47
	v_fmac_f32_e32 v70, v25, v45
	v_fmac_f32_e32 v70, v24, v43
	v_fmac_f32_e32 v70, v23, v50
	v_fmac_f32_e32 v70, v28, v49
	v_fmac_f32_e32 v70, v31, v48
	v_fmac_f32_e32 v70, v30, v46
	v_fmac_f32_e32 v70, v29, v44
	v_fmac_f32_e32 v70, v34, v57
	v_fmac_f32_e32 v70, v33, v55
	v_fmac_f32_e32 v70, v32, v53
	v_lshl_add_u32 v71, v74, 10, v36
	ds_write_b32 v71, v70 offset:49152
	v_fma_f32 v70, v3, v81, v35
	v_fmac_f32_e32 v70, v2, v82
	v_fmac_f32_e32 v70, v1, v83
	v_fmac_f32_e32 v70, v0, v86
	v_fmac_f32_e32 v70, v7, v87
	v_fmac_f32_e32 v70, v6, v72
	v_fmac_f32_e32 v70, v5, v63
	v_fmac_f32_e32 v70, v4, v64
	v_fmac_f32_e32 v70, v18, v65
	v_fmac_f32_e32 v70, v17, v66
	v_fmac_f32_e32 v70, v16, v67
	v_fmac_f32_e32 v70, v15, v68
	v_fmac_f32_e32 v70, v14, v69
	v_fmac_f32_e32 v70, v13, v37
	v_fmac_f32_e32 v70, v12, v42
	v_fmac_f32_e32 v70, v9, v41
	v_fmac_f32_e32 v70, v19, v40
	v_fmac_f32_e32 v70, v22, v39
	v_fmac_f32_e32 v70, v21, v38
	v_fmac_f32_e32 v70, v20, v47
	v_fmac_f32_e32 v70, v26, v45
	v_fmac_f32_e32 v70, v25, v43
	v_fmac_f32_e32 v70, v24, v50
	v_fmac_f32_e32 v70, v23, v49
	v_fmac_f32_e32 v70, v28, v48
	v_fmac_f32_e32 v70, v31, v46
	v_fmac_f32_e32 v70, v30, v44
	v_fmac_f32_e32 v70, v29, v57
	v_fmac_f32_e32 v70, v34, v55
	s_waitcnt lgkmcnt(7)
	v_lshlrev_b32_e32 v60, 16, v54
	v_fmac_f32_e32 v70, v33, v53
	v_fmac_f32_e32 v70, v32, v60
	v_lshl_add_u32 v71, v75, 10, v36
	ds_write_b32 v71, v70 offset:49152
	v_fma_f32 v70, v3, v82, v35
	v_fmac_f32_e32 v70, v2, v83
	v_fmac_f32_e32 v70, v1, v86
	v_fmac_f32_e32 v70, v0, v87
	v_fmac_f32_e32 v70, v7, v72
	v_fmac_f32_e32 v70, v6, v63
	v_fmac_f32_e32 v70, v5, v64
	v_fmac_f32_e32 v70, v4, v65
	v_fmac_f32_e32 v70, v18, v66
	v_fmac_f32_e32 v70, v17, v67
	v_fmac_f32_e32 v70, v16, v68
	v_fmac_f32_e32 v70, v15, v69
	v_fmac_f32_e32 v70, v14, v37
	v_fmac_f32_e32 v70, v13, v42
	v_fmac_f32_e32 v70, v12, v41
	v_fmac_f32_e32 v70, v9, v40
	v_fmac_f32_e32 v70, v19, v39
	v_fmac_f32_e32 v70, v22, v38
	v_fmac_f32_e32 v70, v21, v47
	v_fmac_f32_e32 v70, v20, v45
	v_fmac_f32_e32 v70, v26, v43
	v_fmac_f32_e32 v70, v25, v50
	v_fmac_f32_e32 v70, v24, v49
	v_fmac_f32_e32 v70, v23, v48
	v_fmac_f32_e32 v70, v28, v46
	v_fmac_f32_e32 v70, v31, v44
	v_fmac_f32_e32 v70, v30, v57
	v_fmac_f32_e32 v70, v29, v55
	v_fmac_f32_e32 v70, v34, v53
	s_waitcnt lgkmcnt(7)
	v_lshlrev_b32_e32 v59, 16, v56
	v_fmac_f32_e32 v70, v33, v60
	v_fmac_f32_e32 v70, v32, v59
	v_lshl_add_u32 v71, v76, 10, v36
	ds_write_b32 v71, v70 offset:49152
	v_fma_f32 v70, v3, v83, v35
	v_fmac_f32_e32 v70, v2, v86
	v_fmac_f32_e32 v70, v1, v87
	v_fmac_f32_e32 v70, v0, v72
	v_fmac_f32_e32 v70, v7, v63
	v_fmac_f32_e32 v70, v6, v64
	v_fmac_f32_e32 v70, v5, v65
	v_fmac_f32_e32 v70, v4, v66
	v_fmac_f32_e32 v70, v18, v67
	v_fmac_f32_e32 v70, v17, v68
	v_fmac_f32_e32 v70, v16, v69
	v_fmac_f32_e32 v70, v15, v37
	v_fmac_f32_e32 v70, v14, v42
	v_fmac_f32_e32 v70, v13, v41
	v_fmac_f32_e32 v70, v12, v40
	v_fmac_f32_e32 v70, v9, v39
	v_fmac_f32_e32 v70, v19, v38
	v_fmac_f32_e32 v70, v22, v47
	v_fmac_f32_e32 v70, v21, v45
	v_fmac_f32_e32 v70, v20, v43
	v_fmac_f32_e32 v70, v26, v50
	v_fmac_f32_e32 v70, v25, v49
	v_fmac_f32_e32 v70, v24, v48
	v_fmac_f32_e32 v70, v23, v46
	v_fmac_f32_e32 v70, v28, v44
	v_fmac_f32_e32 v70, v31, v57
	v_fmac_f32_e32 v70, v30, v55
	v_fmac_f32_e32 v70, v29, v53
	v_fmac_f32_e32 v70, v34, v60
	s_waitcnt lgkmcnt(7)
	v_lshlrev_b32_e32 v58, 16, v58
	v_fmac_f32_e32 v70, v33, v59
	v_fmac_f32_e32 v70, v32, v58
	v_lshl_add_u32 v71, v77, 10, v36
	ds_write_b32 v71, v70 offset:49152
	v_fma_f32 v70, v3, v86, v35
	v_fmac_f32_e32 v70, v2, v87
	v_fmac_f32_e32 v70, v1, v72
	v_fmac_f32_e32 v70, v0, v63
	v_fmac_f32_e32 v70, v7, v64
	v_fmac_f32_e32 v70, v6, v65
	v_fmac_f32_e32 v70, v5, v66
	v_fmac_f32_e32 v70, v4, v67
	v_fmac_f32_e32 v70, v18, v68
	v_fmac_f32_e32 v70, v17, v69
	v_fmac_f32_e32 v70, v16, v37
	v_fmac_f32_e32 v70, v15, v42
	v_fmac_f32_e32 v70, v14, v41
	v_fmac_f32_e32 v70, v13, v40
	v_fmac_f32_e32 v70, v12, v39
	v_fmac_f32_e32 v70, v9, v38
	v_fmac_f32_e32 v70, v19, v47
	v_fmac_f32_e32 v70, v22, v45
	v_fmac_f32_e32 v70, v21, v43
	v_fmac_f32_e32 v70, v20, v50
	v_fmac_f32_e32 v70, v26, v49
	v_fmac_f32_e32 v70, v25, v48
	v_fmac_f32_e32 v70, v24, v46
	v_fmac_f32_e32 v70, v23, v44
	v_fmac_f32_e32 v70, v28, v57
	v_fmac_f32_e32 v70, v31, v55
	v_fmac_f32_e32 v70, v30, v53
	v_fmac_f32_e32 v70, v29, v60
	v_fmac_f32_e32 v70, v34, v59
	s_waitcnt lgkmcnt(7)
	v_lshlrev_b32_e32 v56, 16, v88
	v_fmac_f32_e32 v70, v33, v58
	v_fmac_f32_e32 v70, v32, v56
	v_lshl_add_u32 v71, v84, 10, v36
	ds_write_b32 v71, v70 offset:49152
	v_fma_f32 v70, v3, v87, v35
	v_fmac_f32_e32 v70, v2, v72
	v_fmac_f32_e32 v70, v1, v63
	v_fmac_f32_e32 v70, v0, v64
	v_fmac_f32_e32 v70, v7, v65
	v_fmac_f32_e32 v70, v6, v66
	v_fmac_f32_e32 v70, v5, v67
	v_fmac_f32_e32 v70, v4, v68
	v_fmac_f32_e32 v70, v18, v69
	v_fmac_f32_e32 v70, v17, v37
	v_fmac_f32_e32 v70, v16, v42
	v_fmac_f32_e32 v70, v15, v41
	v_fmac_f32_e32 v70, v14, v40
	v_fmac_f32_e32 v70, v13, v39
	v_fmac_f32_e32 v70, v12, v38
	v_fmac_f32_e32 v70, v9, v47
	v_fmac_f32_e32 v70, v19, v45
	v_fmac_f32_e32 v70, v22, v43
	v_fmac_f32_e32 v70, v21, v50
	v_fmac_f32_e32 v70, v20, v49
	v_fmac_f32_e32 v70, v26, v48
	v_fmac_f32_e32 v70, v25, v46
	v_fmac_f32_e32 v70, v24, v44
	v_fmac_f32_e32 v70, v23, v57
	v_fmac_f32_e32 v70, v28, v55
	v_fmac_f32_e32 v70, v31, v53
	v_fmac_f32_e32 v70, v30, v60
	v_fmac_f32_e32 v70, v29, v59
	v_fmac_f32_e32 v70, v34, v58
	s_waitcnt lgkmcnt(7)
	v_lshlrev_b32_e32 v54, 16, v89
	v_fmac_f32_e32 v70, v33, v56
	v_fmac_f32_e32 v70, v32, v54
	v_lshl_add_u32 v63, v85, 10, v36
	v_or_b32_e32 v75, 25, v61
	v_or_b32_e32 v71, 27, v61
	ds_write_b32 v63, v70 offset:49152
	v_lshl_add_u32 v63, v75, 9, v62
	v_lshl_add_u32 v65, v71, 9, v62
	ds_read_u16 v63, v63
	ds_read_u16 v65, v65
	v_or_b32_e32 v73, 26, v61
	v_lshl_add_u32 v64, v73, 9, v62
	ds_read_u16 v64, v64
	v_or_b32_e32 v69, 28, v61
	v_or_b32_e32 v67, 29, v61
	v_lshl_add_u32 v66, v69, 9, v62
	v_lshl_add_u32 v68, v67, 9, v62
	ds_read_u16 v66, v66
	ds_read_u16 v68, v68
	s_waitcnt lgkmcnt(3)
	v_lshlrev_b32_e32 v74, 16, v65
	v_or_b32_e32 v65, 30, v61
	v_lshl_add_u32 v61, v65, 9, v62
	v_lshlrev_b32_e32 v77, 16, v63
	ds_read_u16 v63, v61
	v_fma_f32 v52, v3, v52, v35
	s_waitcnt lgkmcnt(3)
	v_lshlrev_b32_e32 v76, 16, v64
	v_fmac_f32_e32 v52, v2, v77
	v_or_b32_e32 v61, 31, v27
	v_fmac_f32_e32 v52, v1, v76
	s_waitcnt lgkmcnt(2)
	v_lshlrev_b32_e32 v72, 16, v66
	v_lshl_add_u32 v62, v61, 9, v62
	v_fmac_f32_e32 v52, v0, v74
	s_waitcnt lgkmcnt(1)
	v_lshlrev_b32_e32 v70, 16, v68
	ds_read_u16 v62, v62
	ds_read_u16 v64, v78 offset:27648
	ds_read_u16 v79, v78 offset:28160
	ds_read_u16 v80, v78 offset:28672
	v_fmac_f32_e32 v52, v7, v72
	s_waitcnt lgkmcnt(4)
	v_lshlrev_b32_e32 v68, 16, v63
	v_fmac_f32_e32 v52, v6, v70
	s_waitcnt lgkmcnt(3)
	v_lshlrev_b32_e32 v66, 16, v62
	v_fmac_f32_e32 v52, v5, v68
	v_fmac_f32_e32 v52, v4, v66
	v_fmac_f32_e32 v52, v18, v37
	v_fmac_f32_e32 v52, v17, v42
	v_fmac_f32_e32 v52, v16, v41
	v_fmac_f32_e32 v52, v15, v40
	v_fmac_f32_e32 v52, v14, v39
	v_fmac_f32_e32 v52, v13, v38
	v_fmac_f32_e32 v52, v12, v47
	v_fmac_f32_e32 v52, v9, v45
	v_fmac_f32_e32 v52, v19, v43
	v_fmac_f32_e32 v52, v22, v50
	v_fmac_f32_e32 v52, v21, v49
	v_fmac_f32_e32 v52, v20, v48
	v_fmac_f32_e32 v52, v26, v46
	v_fmac_f32_e32 v52, v25, v44
	v_fmac_f32_e32 v52, v24, v57
	v_fmac_f32_e32 v52, v23, v55
	v_fmac_f32_e32 v52, v28, v53
	v_fmac_f32_e32 v52, v31, v60
	v_fmac_f32_e32 v52, v30, v59
	v_fmac_f32_e32 v52, v29, v58
	v_fmac_f32_e32 v52, v34, v56
	s_waitcnt lgkmcnt(2)
	v_lshlrev_b32_e32 v64, 16, v64
	v_fmac_f32_e32 v52, v33, v54
	v_fmac_f32_e32 v52, v32, v64
	s_waitcnt lgkmcnt(1)
	v_lshlrev_b32_e32 v63, 16, v79
	s_waitcnt lgkmcnt(0)
	v_lshlrev_b32_e32 v62, 16, v80
	ds_read_u16 v79, v78 offset:29184
	ds_read_u16 v80, v78 offset:29696
	ds_read_u16 v81, v78 offset:30208
	ds_read_u16 v82, v78 offset:30720
	ds_read_u16 v78, v78 offset:31232
	ds_write_b32 v51, v52 offset:49152
	v_fma_f32 v51, v3, v77, v35
	v_fmac_f32_e32 v51, v2, v76
	v_fmac_f32_e32 v51, v1, v74
	v_fmac_f32_e32 v51, v0, v72
	v_fmac_f32_e32 v51, v7, v70
	v_fmac_f32_e32 v51, v6, v68
	v_fmac_f32_e32 v51, v5, v66
	v_fmac_f32_e32 v51, v4, v37
	v_fmac_f32_e32 v51, v18, v42
	v_fmac_f32_e32 v51, v17, v41
	v_fmac_f32_e32 v51, v16, v40
	v_fmac_f32_e32 v51, v15, v39
	v_fmac_f32_e32 v51, v14, v38
	v_fmac_f32_e32 v51, v13, v47
	v_fmac_f32_e32 v51, v12, v45
	v_fmac_f32_e32 v51, v9, v43
	v_fmac_f32_e32 v51, v19, v50
	v_fmac_f32_e32 v51, v22, v49
	v_fmac_f32_e32 v51, v21, v48
	v_fmac_f32_e32 v51, v20, v46
	v_fmac_f32_e32 v51, v26, v44
	v_fmac_f32_e32 v51, v25, v57
	v_fmac_f32_e32 v51, v24, v55
	v_fmac_f32_e32 v51, v23, v53
	v_fmac_f32_e32 v51, v28, v60
	v_fmac_f32_e32 v51, v31, v59
	v_fmac_f32_e32 v51, v30, v58
	v_fmac_f32_e32 v51, v29, v56
	v_fmac_f32_e32 v51, v34, v54
	v_fmac_f32_e32 v51, v33, v64
	v_fmac_f32_e32 v51, v32, v63
	v_lshl_add_u32 v52, v75, 10, v36
	ds_write_b32 v52, v51 offset:49152
	v_fma_f32 v51, v3, v76, v35
	v_fmac_f32_e32 v51, v2, v74
	v_fmac_f32_e32 v51, v1, v72
	v_fmac_f32_e32 v51, v0, v70
	v_fmac_f32_e32 v51, v7, v68
	v_fmac_f32_e32 v51, v6, v66
	v_fmac_f32_e32 v51, v5, v37
	v_fmac_f32_e32 v51, v4, v42
	v_fmac_f32_e32 v51, v18, v41
	v_fmac_f32_e32 v51, v17, v40
	v_fmac_f32_e32 v51, v16, v39
	v_fmac_f32_e32 v51, v15, v38
	v_fmac_f32_e32 v51, v14, v47
	v_fmac_f32_e32 v51, v13, v45
	v_fmac_f32_e32 v51, v12, v43
	v_fmac_f32_e32 v51, v9, v50
	v_fmac_f32_e32 v51, v19, v49
	v_fmac_f32_e32 v51, v22, v48
	v_fmac_f32_e32 v51, v21, v46
	v_fmac_f32_e32 v51, v20, v44
	v_fmac_f32_e32 v51, v26, v57
	v_fmac_f32_e32 v51, v25, v55
	v_fmac_f32_e32 v51, v24, v53
	v_fmac_f32_e32 v51, v23, v60
	v_fmac_f32_e32 v51, v28, v59
	v_fmac_f32_e32 v51, v31, v58
	v_fmac_f32_e32 v51, v30, v56
	v_fmac_f32_e32 v51, v29, v54
	v_fmac_f32_e32 v51, v34, v64
	v_fmac_f32_e32 v51, v33, v63
	v_fmac_f32_e32 v51, v32, v62
	v_lshl_add_u32 v52, v73, 10, v36
	ds_write_b32 v52, v51 offset:49152
	v_fma_f32 v51, v3, v74, v35
	v_fmac_f32_e32 v51, v2, v72
	v_fmac_f32_e32 v51, v1, v70
	v_fmac_f32_e32 v51, v0, v68
	v_fmac_f32_e32 v51, v7, v66
	v_fmac_f32_e32 v51, v6, v37
	v_fmac_f32_e32 v51, v5, v42
	v_fmac_f32_e32 v51, v4, v41
	v_fmac_f32_e32 v51, v18, v40
	v_fmac_f32_e32 v51, v17, v39
	v_fmac_f32_e32 v51, v16, v38
	v_fmac_f32_e32 v51, v15, v47
	v_fmac_f32_e32 v51, v14, v45
	v_fmac_f32_e32 v51, v13, v43
	v_fmac_f32_e32 v51, v12, v50
	v_fmac_f32_e32 v51, v9, v49
	v_fmac_f32_e32 v51, v19, v48
	v_fmac_f32_e32 v51, v22, v46
	v_fmac_f32_e32 v51, v21, v44
	v_fmac_f32_e32 v51, v20, v57
	v_fmac_f32_e32 v51, v26, v55
	v_fmac_f32_e32 v51, v25, v53
	v_fmac_f32_e32 v51, v24, v60
	v_fmac_f32_e32 v51, v23, v59
	v_fmac_f32_e32 v51, v28, v58
	v_fmac_f32_e32 v51, v31, v56
	v_fmac_f32_e32 v51, v30, v54
	v_fmac_f32_e32 v51, v29, v64
	v_fmac_f32_e32 v51, v34, v63
	s_waitcnt lgkmcnt(7)
	v_lshlrev_b32_e32 v84, 16, v79
	v_fmac_f32_e32 v51, v33, v62
	v_fmac_f32_e32 v51, v32, v84
	v_lshl_add_u32 v52, v71, 10, v36
	ds_write_b32 v52, v51 offset:49152
	v_fma_f32 v51, v3, v72, v35
	v_fmac_f32_e32 v51, v2, v70
	v_fmac_f32_e32 v51, v1, v68
	v_fmac_f32_e32 v51, v0, v66
	v_fmac_f32_e32 v51, v7, v37
	v_fmac_f32_e32 v51, v6, v42
	v_fmac_f32_e32 v51, v5, v41
	v_fmac_f32_e32 v51, v4, v40
	v_fmac_f32_e32 v51, v18, v39
	v_fmac_f32_e32 v51, v17, v38
	v_fmac_f32_e32 v51, v16, v47
	v_fmac_f32_e32 v51, v15, v45
	v_fmac_f32_e32 v51, v14, v43
	v_fmac_f32_e32 v51, v13, v50
	v_fmac_f32_e32 v51, v12, v49
	v_fmac_f32_e32 v51, v9, v48
	v_fmac_f32_e32 v51, v19, v46
	v_fmac_f32_e32 v51, v22, v44
	v_fmac_f32_e32 v51, v21, v57
	v_fmac_f32_e32 v51, v20, v55
	v_fmac_f32_e32 v51, v26, v53
	v_fmac_f32_e32 v51, v25, v60
	v_fmac_f32_e32 v51, v24, v59
	v_fmac_f32_e32 v51, v23, v58
	v_fmac_f32_e32 v51, v28, v56
	v_fmac_f32_e32 v51, v31, v54
	v_fmac_f32_e32 v51, v30, v64
	v_fmac_f32_e32 v51, v29, v63
	v_fmac_f32_e32 v51, v34, v62
	s_waitcnt lgkmcnt(7)
	v_lshlrev_b32_e32 v83, 16, v80
	v_fmac_f32_e32 v51, v33, v84
	v_fmac_f32_e32 v51, v32, v83
	v_lshl_add_u32 v52, v69, 10, v36
	ds_write_b32 v52, v51 offset:49152
	v_fma_f32 v51, v3, v70, v35
	v_fmac_f32_e32 v51, v2, v68
	v_fmac_f32_e32 v51, v1, v66
	v_fmac_f32_e32 v51, v0, v37
	v_fmac_f32_e32 v51, v7, v42
	v_fmac_f32_e32 v51, v6, v41
	v_fmac_f32_e32 v51, v5, v40
	v_fmac_f32_e32 v51, v4, v39
	v_fmac_f32_e32 v51, v18, v38
	v_fmac_f32_e32 v51, v17, v47
	v_fmac_f32_e32 v51, v16, v45
	v_fmac_f32_e32 v51, v15, v43
	v_fmac_f32_e32 v51, v14, v50
	v_fmac_f32_e32 v51, v13, v49
	v_fmac_f32_e32 v51, v12, v48
	v_fmac_f32_e32 v51, v9, v46
	v_fmac_f32_e32 v51, v19, v44
	v_fmac_f32_e32 v51, v22, v57
	v_fmac_f32_e32 v51, v21, v55
	v_fmac_f32_e32 v51, v20, v53
	v_fmac_f32_e32 v51, v26, v60
	v_fmac_f32_e32 v51, v25, v59
	v_fmac_f32_e32 v51, v24, v58
	v_fmac_f32_e32 v51, v23, v56
	v_fmac_f32_e32 v51, v28, v54
	v_fmac_f32_e32 v51, v31, v64
	v_fmac_f32_e32 v51, v30, v63
	v_fmac_f32_e32 v51, v29, v62
	v_fmac_f32_e32 v51, v34, v84
	s_waitcnt lgkmcnt(7)
	v_lshlrev_b32_e32 v80, 16, v81
	v_fmac_f32_e32 v51, v33, v83
	v_fmac_f32_e32 v51, v32, v80
	v_lshl_add_u32 v52, v67, 10, v36
	ds_write_b32 v52, v51 offset:49152
	v_fma_f32 v51, v3, v68, v35
	v_fmac_f32_e32 v35, v3, v66
	v_fmac_f32_e32 v51, v2, v66
	v_fmac_f32_e32 v35, v2, v37
	v_fmac_f32_e32 v51, v1, v37
	v_fmac_f32_e32 v35, v1, v42
	v_fmac_f32_e32 v51, v0, v42
	v_fmac_f32_e32 v35, v0, v41
	v_fmac_f32_e32 v51, v7, v41
	v_fmac_f32_e32 v35, v7, v40
	v_fmac_f32_e32 v51, v6, v40
	v_fmac_f32_e32 v35, v6, v39
	v_fmac_f32_e32 v51, v5, v39
	v_fmac_f32_e32 v35, v5, v38
	v_fmac_f32_e32 v51, v4, v38
	v_fmac_f32_e32 v35, v4, v47
	v_fmac_f32_e32 v51, v18, v47
	v_fmac_f32_e32 v35, v18, v45
	v_fmac_f32_e32 v51, v17, v45
	v_fmac_f32_e32 v35, v17, v43
	v_fmac_f32_e32 v51, v16, v43
	v_fmac_f32_e32 v35, v16, v50
	v_fmac_f32_e32 v51, v15, v50
	v_fmac_f32_e32 v35, v15, v49
	v_fmac_f32_e32 v51, v14, v49
	v_fmac_f32_e32 v35, v14, v48
	v_fmac_f32_e32 v51, v13, v48
	v_fmac_f32_e32 v35, v13, v46
	v_fmac_f32_e32 v51, v12, v46
	v_fmac_f32_e32 v35, v12, v44
	v_fmac_f32_e32 v51, v9, v44
	v_fmac_f32_e32 v35, v9, v57
	v_fmac_f32_e32 v51, v19, v57
	v_fmac_f32_e32 v35, v19, v55
	v_fmac_f32_e32 v51, v22, v55
	v_fmac_f32_e32 v35, v22, v53
	v_fmac_f32_e32 v51, v21, v53
	v_fmac_f32_e32 v35, v21, v60
	v_fmac_f32_e32 v51, v20, v60
	v_fmac_f32_e32 v35, v20, v59
	v_fmac_f32_e32 v51, v26, v59
	v_fmac_f32_e32 v35, v26, v58
	v_fmac_f32_e32 v51, v25, v58
	v_fmac_f32_e32 v35, v25, v56
	v_fmac_f32_e32 v51, v24, v56
	v_fmac_f32_e32 v35, v24, v54
	v_fmac_f32_e32 v51, v23, v54
	v_fmac_f32_e32 v35, v23, v64
	v_fmac_f32_e32 v51, v28, v64
	v_fmac_f32_e32 v35, v28, v63
	v_fmac_f32_e32 v51, v31, v63
	v_fmac_f32_e32 v35, v31, v62
	v_fmac_f32_e32 v51, v30, v62
	v_fmac_f32_e32 v35, v30, v84
	v_fmac_f32_e32 v51, v29, v84
	v_fmac_f32_e32 v35, v29, v83
	s_waitcnt lgkmcnt(7)
	v_lshlrev_b32_e32 v79, 16, v82
	v_fmac_f32_e32 v51, v34, v83
	v_fmac_f32_e32 v35, v34, v80
	s_waitcnt lgkmcnt(6)
	v_lshlrev_b32_e32 v78, 16, v78
	v_fmac_f32_e32 v51, v33, v80
	v_fmac_f32_e32 v35, v33, v79
	v_fmac_f32_e32 v51, v32, v79
	v_lshl_add_u32 v52, v65, 10, v36
	v_fmac_f32_e32 v35, v32, v78
	v_lshl_add_u32 v0, v61, 10, v36
	ds_write_b32 v52, v51 offset:49152
	ds_write_b32 v0, v35 offset:49152
	v_lshlrev_b32_e32 v0, 4, v8
	v_and_b32_e32 v4, 0x3f0, v0
	s_waitcnt lgkmcnt(0)
	s_barrier
	v_mov_b32_e32 v0, v116
	v_mov_b32_e32 v1, v117
	v_mov_b32_e32 v2, v118
	v_mov_b32_e32 v3, v119
	s_nop 0
	v_mov_b32_e32 v4, v120
	v_mov_b32_e32 v5, v121
	v_mov_b32_e32 v6, v122
	v_mov_b32_e32 v7, v123
	v_and_b32_e32 v12, -8, v27
	v_ashrrev_i32_e32 v13, 31, v12
	v_lshl_add_u64 v[12:13], s[8:9], 0, v[12:13]
	v_lshlrev_b64 v[12:13], 11, v[12:13]
	v_and_b32_e32 v14, 63, v8
	v_lshl_or_b32 v12, v14, 3, v12
	v_lshl_add_u64 v[8:9], s[24:25], 0, v[12:13]
	v_lshlrev_b32_e32 v12, 10, v27
	v_lshlrev_b32_e32 v13, 4, v14
	s_movk_i32 s8, 0xe000
	v_and_or_b32 v12, v12, s8, v13
	s_add_i32 s8, 0, 0xc000
	v_add_u32_e32 v12, s8, v12
	s_waitcnt vmcnt(0)
	ds_read_b128 v[28:31], v12
	ds_read_b128 v[32:35], v12 offset:1024
	ds_read_b128 v[38:41], v12 offset:2048
	ds_read_b128 v[44:47], v12 offset:3072
	ds_read_b128 v[54:57], v12 offset:4096
	ds_read_b128 v[62:65], v12 offset:5120
	ds_read_b128 v[78:81], v12 offset:6144
	ds_read_b128 v[88:91], v12 offset:7168
	s_mov_b64 s[8:9], 0x800
	s_waitcnt lgkmcnt(0)
	v_add_f32_e32 v48, v29, v28
	v_add_f32_e32 v53, v30, v31
	v_add_f32_e32 v13, v48, v53
	v_add_f32_e32 v48, v33, v32
	v_add_f32_e32 v53, v34, v35
	v_add_f32_e32 v14, v48, v53
	v_add_f32_e32 v48, v39, v38
	v_add_f32_e32 v53, v40, v41
	v_add_f32_e32 v15, v48, v53
	v_add_f32_e32 v48, v45, v44
	v_add_f32_e32 v53, v46, v47
	v_add_f32_e32 v16, v48, v53
	v_add_f32_e32 v48, v55, v54
	v_add_f32_e32 v53, v56, v57
	v_add_f32_e32 v17, v48, v53
	v_add_f32_e32 v48, v63, v62
	v_add_f32_e32 v53, v64, v65
	v_add_f32_e32 v18, v48, v53
	v_add_f32_e32 v48, v79, v78
	v_add_f32_e32 v53, v80, v81
	v_add_f32_e32 v19, v48, v53
	v_add_f32_e32 v48, v89, v88
	v_add_f32_e32 v53, v90, v91
	v_add_f32_e32 v20, v48, v53
	ds_bpermute_b32 v21, v202, v13
	ds_bpermute_b32 v22, v202, v14
	ds_bpermute_b32 v23, v202, v15
	ds_bpermute_b32 v24, v202, v16
	ds_bpermute_b32 v25, v202, v17
	ds_bpermute_b32 v26, v202, v18
	ds_bpermute_b32 v37, v202, v19
	ds_bpermute_b32 v43, v202, v20
	s_waitcnt lgkmcnt(0)
	v_add_f32_e32 v13, v13, v21
	v_add_f32_e32 v14, v14, v22
	v_add_f32_e32 v15, v15, v23
	v_add_f32_e32 v16, v16, v24
	v_add_f32_e32 v17, v17, v25
	v_add_f32_e32 v18, v18, v26
	v_add_f32_e32 v19, v19, v37
	v_add_f32_e32 v20, v20, v43
	ds_bpermute_b32 v21, v203, v13
	ds_bpermute_b32 v22, v203, v14
	ds_bpermute_b32 v23, v203, v15
	ds_bpermute_b32 v24, v203, v16
	ds_bpermute_b32 v25, v203, v17
	ds_bpermute_b32 v26, v203, v18
	ds_bpermute_b32 v37, v203, v19
	ds_bpermute_b32 v43, v203, v20
	s_waitcnt lgkmcnt(0)
	v_add_f32_e32 v13, v13, v21
	v_add_f32_e32 v14, v14, v22
	v_add_f32_e32 v15, v15, v23
	v_add_f32_e32 v16, v16, v24
	v_add_f32_e32 v17, v17, v25
	v_add_f32_e32 v18, v18, v26
	v_add_f32_e32 v19, v19, v37
	v_add_f32_e32 v20, v20, v43
	ds_bpermute_b32 v21, v204, v13
	ds_bpermute_b32 v22, v204, v14
	ds_bpermute_b32 v23, v204, v15
	ds_bpermute_b32 v24, v204, v16
	ds_bpermute_b32 v25, v204, v17
	ds_bpermute_b32 v26, v204, v18
	ds_bpermute_b32 v37, v204, v19
	ds_bpermute_b32 v43, v204, v20
	s_waitcnt lgkmcnt(0)
	v_add_f32_e32 v13, v13, v21
	v_add_f32_e32 v14, v14, v22
	v_add_f32_e32 v15, v15, v23
	v_add_f32_e32 v16, v16, v24
	v_add_f32_e32 v17, v17, v25
	v_add_f32_e32 v18, v18, v26
	v_add_f32_e32 v19, v19, v37
	v_add_f32_e32 v20, v20, v43
	ds_bpermute_b32 v21, v205, v13
	ds_bpermute_b32 v22, v205, v14
	ds_bpermute_b32 v23, v205, v15
	ds_bpermute_b32 v24, v205, v16
	ds_bpermute_b32 v25, v205, v17
	ds_bpermute_b32 v26, v205, v18
	ds_bpermute_b32 v37, v205, v19
	ds_bpermute_b32 v43, v205, v20
	s_waitcnt lgkmcnt(0)
	v_add_f32_e32 v13, v13, v21
	v_add_f32_e32 v14, v14, v22
	v_add_f32_e32 v15, v15, v23
	v_add_f32_e32 v16, v16, v24
	v_add_f32_e32 v17, v17, v25
	v_add_f32_e32 v18, v18, v26
	v_add_f32_e32 v19, v19, v37
	v_add_f32_e32 v20, v20, v43
	ds_bpermute_b32 v21, v206, v13
	ds_bpermute_b32 v22, v206, v14
	ds_bpermute_b32 v23, v206, v15
	ds_bpermute_b32 v24, v206, v16
	ds_bpermute_b32 v25, v206, v17
	ds_bpermute_b32 v26, v206, v18
	ds_bpermute_b32 v37, v206, v19
	ds_bpermute_b32 v43, v206, v20
	s_waitcnt lgkmcnt(0)
	v_add_f32_e32 v13, v13, v21
	v_add_f32_e32 v14, v14, v22
	v_add_f32_e32 v15, v15, v23
	v_add_f32_e32 v16, v16, v24
	v_add_f32_e32 v17, v17, v25
	v_add_f32_e32 v18, v18, v26
	v_add_f32_e32 v19, v19, v37
	v_add_f32_e32 v20, v20, v43
	ds_bpermute_b32 v21, v11, v13
	ds_bpermute_b32 v22, v11, v14
	ds_bpermute_b32 v23, v11, v15
	ds_bpermute_b32 v24, v11, v16
	ds_bpermute_b32 v25, v11, v17
	ds_bpermute_b32 v26, v11, v18
	ds_bpermute_b32 v37, v11, v19
	ds_bpermute_b32 v43, v11, v20
	s_waitcnt lgkmcnt(0)
	v_add_f32_e32 v13, v13, v21
	v_add_f32_e32 v14, v14, v22
	v_add_f32_e32 v15, v15, v23
	v_add_f32_e32 v16, v16, v24
	v_add_f32_e32 v17, v17, v25
	v_add_f32_e32 v18, v18, v26
	v_add_f32_e32 v19, v19, v37
	v_add_f32_e32 v20, v20, v43
	v_fmamk_f32 v28, v13, 0xbb800000, v28
	v_fmamk_f32 v29, v13, 0xbb800000, v29
	v_fmamk_f32 v30, v13, 0xbb800000, v30
	v_fmamk_f32 v31, v13, 0xbb800000, v31
	v_fmamk_f32 v32, v14, 0xbb800000, v32
	v_fmamk_f32 v33, v14, 0xbb800000, v33
	v_fmamk_f32 v34, v14, 0xbb800000, v34
	v_fmamk_f32 v35, v14, 0xbb800000, v35
	v_fmamk_f32 v38, v15, 0xbb800000, v38
	v_fmamk_f32 v39, v15, 0xbb800000, v39
	v_fmamk_f32 v40, v15, 0xbb800000, v40
	v_fmamk_f32 v41, v15, 0xbb800000, v41
	v_fmamk_f32 v44, v16, 0xbb800000, v44
	v_fmamk_f32 v45, v16, 0xbb800000, v45
	v_fmamk_f32 v46, v16, 0xbb800000, v46
	v_fmamk_f32 v47, v16, 0xbb800000, v47
	v_fmamk_f32 v54, v17, 0xbb800000, v54
	v_fmamk_f32 v55, v17, 0xbb800000, v55
	v_fmamk_f32 v56, v17, 0xbb800000, v56
	v_fmamk_f32 v57, v17, 0xbb800000, v57
	v_fmamk_f32 v62, v18, 0xbb800000, v62
	v_fmamk_f32 v63, v18, 0xbb800000, v63
	v_fmamk_f32 v64, v18, 0xbb800000, v64
	v_fmamk_f32 v65, v18, 0xbb800000, v65
	v_fmamk_f32 v78, v19, 0xbb800000, v78
	v_fmamk_f32 v79, v19, 0xbb800000, v79
	v_fmamk_f32 v80, v19, 0xbb800000, v80
	v_fmamk_f32 v81, v19, 0xbb800000, v81
	v_fmamk_f32 v88, v20, 0xbb800000, v88
	v_fmamk_f32 v89, v20, 0xbb800000, v89
	v_fmamk_f32 v90, v20, 0xbb800000, v90
	v_fmamk_f32 v91, v20, 0xbb800000, v91
	v_mul_f32_e32 v48, v29, v29
	v_mul_f32_e32 v53, v30, v30
	v_mul_f32_e32 v21, v28, v28
	v_mul_f32_e32 v13, v31, v31
	v_add_f32_e32 v48, v48, v21
	v_add_f32_e32 v53, v53, v13
	v_add_f32_e32 v13, v48, v53
	v_mul_f32_e32 v48, v33, v33
	v_mul_f32_e32 v53, v34, v34
	v_mul_f32_e32 v22, v32, v32
	v_mul_f32_e32 v14, v35, v35
	v_add_f32_e32 v48, v48, v22
	v_add_f32_e32 v53, v53, v14
	v_add_f32_e32 v14, v48, v53
	v_mul_f32_e32 v48, v39, v39
	v_mul_f32_e32 v53, v40, v40
	v_mul_f32_e32 v23, v38, v38
	v_mul_f32_e32 v15, v41, v41
	v_add_f32_e32 v48, v48, v23
	v_add_f32_e32 v53, v53, v15
	v_add_f32_e32 v15, v48, v53
	v_mul_f32_e32 v48, v45, v45
	v_mul_f32_e32 v53, v46, v46
	v_mul_f32_e32 v24, v44, v44
	v_mul_f32_e32 v16, v47, v47
	v_add_f32_e32 v48, v48, v24
	v_add_f32_e32 v53, v53, v16
	v_add_f32_e32 v16, v48, v53
	v_mul_f32_e32 v48, v55, v55
	v_mul_f32_e32 v53, v56, v56
	v_mul_f32_e32 v25, v54, v54
	v_mul_f32_e32 v17, v57, v57
	v_add_f32_e32 v48, v48, v25
	v_add_f32_e32 v53, v53, v17
	v_add_f32_e32 v17, v48, v53
	v_mul_f32_e32 v48, v63, v63
	v_mul_f32_e32 v53, v64, v64
	v_mul_f32_e32 v26, v62, v62
	v_mul_f32_e32 v18, v65, v65
	v_add_f32_e32 v48, v48, v26
	v_add_f32_e32 v53, v53, v18
	v_add_f32_e32 v18, v48, v53
	v_mul_f32_e32 v48, v79, v79
	v_mul_f32_e32 v53, v80, v80
	v_mul_f32_e32 v37, v78, v78
	v_mul_f32_e32 v19, v81, v81
	v_add_f32_e32 v48, v48, v37
	v_add_f32_e32 v53, v53, v19
	v_add_f32_e32 v19, v48, v53
	v_mul_f32_e32 v48, v89, v89
	v_mul_f32_e32 v53, v90, v90
	v_mul_f32_e32 v43, v88, v88
	v_mul_f32_e32 v20, v91, v91
	v_add_f32_e32 v48, v48, v43
	v_add_f32_e32 v53, v53, v20
	v_add_f32_e32 v20, v48, v53
	ds_bpermute_b32 v21, v202, v13
	ds_bpermute_b32 v22, v202, v14
	ds_bpermute_b32 v23, v202, v15
	ds_bpermute_b32 v24, v202, v16
	ds_bpermute_b32 v25, v202, v17
	ds_bpermute_b32 v26, v202, v18
	ds_bpermute_b32 v37, v202, v19
	ds_bpermute_b32 v43, v202, v20
	s_waitcnt lgkmcnt(0)
	v_add_f32_e32 v13, v13, v21
	v_add_f32_e32 v14, v14, v22
	v_add_f32_e32 v15, v15, v23
	v_add_f32_e32 v16, v16, v24
	v_add_f32_e32 v17, v17, v25
	v_add_f32_e32 v18, v18, v26
	v_add_f32_e32 v19, v19, v37
	v_add_f32_e32 v20, v20, v43
	ds_bpermute_b32 v21, v203, v13
	ds_bpermute_b32 v22, v203, v14
	ds_bpermute_b32 v23, v203, v15
	ds_bpermute_b32 v24, v203, v16
	ds_bpermute_b32 v25, v203, v17
	ds_bpermute_b32 v26, v203, v18
	ds_bpermute_b32 v37, v203, v19
	ds_bpermute_b32 v43, v203, v20
	s_waitcnt lgkmcnt(0)
	v_add_f32_e32 v13, v13, v21
	v_add_f32_e32 v14, v14, v22
	v_add_f32_e32 v15, v15, v23
	v_add_f32_e32 v16, v16, v24
	v_add_f32_e32 v17, v17, v25
	v_add_f32_e32 v18, v18, v26
	v_add_f32_e32 v19, v19, v37
	v_add_f32_e32 v20, v20, v43
	ds_bpermute_b32 v21, v204, v13
	ds_bpermute_b32 v22, v204, v14
	ds_bpermute_b32 v23, v204, v15
	ds_bpermute_b32 v24, v204, v16
	ds_bpermute_b32 v25, v204, v17
	ds_bpermute_b32 v26, v204, v18
	ds_bpermute_b32 v37, v204, v19
	ds_bpermute_b32 v43, v204, v20
	s_waitcnt lgkmcnt(0)
	v_add_f32_e32 v13, v13, v21
	v_add_f32_e32 v14, v14, v22
	v_add_f32_e32 v15, v15, v23
	v_add_f32_e32 v16, v16, v24
	v_add_f32_e32 v17, v17, v25
	v_add_f32_e32 v18, v18, v26
	v_add_f32_e32 v19, v19, v37
	v_add_f32_e32 v20, v20, v43
	ds_bpermute_b32 v21, v205, v13
	ds_bpermute_b32 v22, v205, v14
	ds_bpermute_b32 v23, v205, v15
	ds_bpermute_b32 v24, v205, v16
	ds_bpermute_b32 v25, v205, v17
	ds_bpermute_b32 v26, v205, v18
	ds_bpermute_b32 v37, v205, v19
	ds_bpermute_b32 v43, v205, v20
	s_waitcnt lgkmcnt(0)
	v_add_f32_e32 v13, v13, v21
	v_add_f32_e32 v14, v14, v22
	v_add_f32_e32 v15, v15, v23
	v_add_f32_e32 v16, v16, v24
	v_add_f32_e32 v17, v17, v25
	v_add_f32_e32 v18, v18, v26
	v_add_f32_e32 v19, v19, v37
	v_add_f32_e32 v20, v20, v43
	ds_bpermute_b32 v21, v206, v13
	ds_bpermute_b32 v22, v206, v14
	ds_bpermute_b32 v23, v206, v15
	ds_bpermute_b32 v24, v206, v16
	ds_bpermute_b32 v25, v206, v17
	ds_bpermute_b32 v26, v206, v18
	ds_bpermute_b32 v37, v206, v19
	ds_bpermute_b32 v43, v206, v20
	s_waitcnt lgkmcnt(0)
	v_add_f32_e32 v13, v13, v21
	v_add_f32_e32 v14, v14, v22
	v_add_f32_e32 v15, v15, v23
	v_add_f32_e32 v16, v16, v24
	v_add_f32_e32 v17, v17, v25
	v_add_f32_e32 v18, v18, v26
	v_add_f32_e32 v19, v19, v37
	v_add_f32_e32 v20, v20, v43
	ds_bpermute_b32 v21, v11, v13
	ds_bpermute_b32 v22, v11, v14
	ds_bpermute_b32 v23, v11, v15
	ds_bpermute_b32 v24, v11, v16
	ds_bpermute_b32 v25, v11, v17
	ds_bpermute_b32 v26, v11, v18
	ds_bpermute_b32 v37, v11, v19
	ds_bpermute_b32 v43, v11, v20
	s_waitcnt lgkmcnt(0)
	v_add_f32_e32 v13, v13, v21
	v_add_f32_e32 v14, v14, v22
	v_add_f32_e32 v15, v15, v23
	v_add_f32_e32 v16, v16, v24
	v_add_f32_e32 v17, v17, v25
	v_add_f32_e32 v18, v18, v26
	v_add_f32_e32 v19, v19, v37
	v_add_f32_e32 v20, v20, v43
	v_fmamk_f32 v13, v13, 0x3b800000, v228
	v_fmamk_f32 v14, v14, 0x3b800000, v228
	v_fmamk_f32 v15, v15, 0x3b800000, v228
	v_fmamk_f32 v16, v16, 0x3b800000, v228
	v_fmamk_f32 v17, v17, 0x3b800000, v228
	v_fmamk_f32 v18, v18, 0x3b800000, v228
	v_fmamk_f32 v19, v19, 0x3b800000, v228
	v_fmamk_f32 v20, v20, 0x3b800000, v228
	v_rsq_f32_e32 v13, v13
	v_rsq_f32_e32 v14, v14
	v_rsq_f32_e32 v15, v15
	v_rsq_f32_e32 v16, v16
	v_rsq_f32_e32 v17, v17
	v_rsq_f32_e32 v18, v18
	v_rsq_f32_e32 v19, v19
	v_rsq_f32_e32 v20, v20
	s_nop 0
	v_mul_f32_e32 v28, v28, v13
	v_mul_f32_e32 v29, v29, v13
	v_mul_f32_e32 v30, v30, v13
	v_mul_f32_e32 v31, v31, v13
	v_mul_f32_e32 v32, v32, v14
	v_mul_f32_e32 v33, v33, v14
	v_mul_f32_e32 v34, v34, v14
	v_mul_f32_e32 v35, v35, v14
	v_mul_f32_e32 v38, v38, v15
	v_mul_f32_e32 v39, v39, v15
	v_mul_f32_e32 v40, v40, v15
	v_mul_f32_e32 v41, v41, v15
	v_mul_f32_e32 v44, v44, v16
	v_mul_f32_e32 v45, v45, v16
	v_mul_f32_e32 v46, v46, v16
	v_mul_f32_e32 v47, v47, v16
	v_mul_f32_e32 v54, v54, v17
	v_mul_f32_e32 v55, v55, v17
	v_mul_f32_e32 v56, v56, v17
	v_mul_f32_e32 v57, v57, v17
	v_mul_f32_e32 v62, v62, v18
	v_mul_f32_e32 v63, v63, v18
	v_mul_f32_e32 v64, v64, v18
	v_mul_f32_e32 v65, v65, v18
	v_mul_f32_e32 v78, v78, v19
	v_mul_f32_e32 v79, v79, v19
	v_mul_f32_e32 v80, v80, v19
	v_mul_f32_e32 v81, v81, v19
	v_mul_f32_e32 v88, v88, v20
	v_mul_f32_e32 v89, v89, v20
	v_mul_f32_e32 v90, v90, v20
	v_mul_f32_e32 v91, v91, v20
	v_fma_f32 v28, v0, v28, v4
	v_fma_f32 v29, v1, v29, v5
	v_fma_f32 v30, v2, v30, v6
	v_fma_f32 v31, v3, v31, v7
	v_fma_f32 v32, v0, v32, v4
	v_fma_f32 v33, v1, v33, v5
	v_fma_f32 v34, v2, v34, v6
	v_fma_f32 v35, v3, v35, v7
	v_fma_f32 v38, v0, v38, v4
	v_fma_f32 v39, v1, v39, v5
	v_fma_f32 v40, v2, v40, v6
	v_fma_f32 v41, v3, v41, v7
	v_fma_f32 v44, v0, v44, v4
	v_fma_f32 v45, v1, v45, v5
	v_fma_f32 v46, v2, v46, v6
	v_fma_f32 v47, v3, v47, v7
	v_fma_f32 v54, v0, v54, v4
	v_fma_f32 v55, v1, v55, v5
	v_fma_f32 v56, v2, v56, v6
	v_fma_f32 v57, v3, v57, v7
	v_fma_f32 v62, v0, v62, v4
	v_fma_f32 v63, v1, v63, v5
	v_fma_f32 v64, v2, v64, v6
	v_fma_f32 v65, v3, v65, v7
	v_fma_f32 v78, v0, v78, v4
	v_fma_f32 v79, v1, v79, v5
	v_fma_f32 v80, v2, v80, v6
	v_fma_f32 v81, v3, v81, v7
	v_fma_f32 v88, v0, v88, v4
	v_fma_f32 v89, v1, v89, v5
	v_fma_f32 v90, v2, v90, v6
	v_fma_f32 v91, v3, v91, v7
	v_mul_f32_e32 v21, 0xbfb8aa3b, v28
	v_mul_f32_e32 v22, 0xbfb8aa3b, v29
	v_mul_f32_e32 v23, 0xbfb8aa3b, v30
	v_mul_f32_e32 v24, 0xbfb8aa3b, v31
	v_mul_f32_e32 v25, 0xbfb8aa3b, v32
	v_mul_f32_e32 v26, 0xbfb8aa3b, v33
	v_mul_f32_e32 v37, 0xbfb8aa3b, v34
	v_mul_f32_e32 v43, 0xbfb8aa3b, v35
	v_mul_f32_e32 v13, 0xbfb8aa3b, v38
	v_mul_f32_e32 v14, 0xbfb8aa3b, v39
	v_mul_f32_e32 v15, 0xbfb8aa3b, v40
	v_mul_f32_e32 v16, 0xbfb8aa3b, v41
	v_mul_f32_e32 v17, 0xbfb8aa3b, v44
	v_mul_f32_e32 v18, 0xbfb8aa3b, v45
	v_mul_f32_e32 v19, 0xbfb8aa3b, v46
	v_mul_f32_e32 v20, 0xbfb8aa3b, v47
	v_exp_f32_e32 v21, v21
	v_exp_f32_e32 v22, v22
	v_exp_f32_e32 v23, v23
	v_exp_f32_e32 v24, v24
	v_exp_f32_e32 v25, v25
	v_exp_f32_e32 v26, v26
	v_exp_f32_e32 v37, v37
	v_exp_f32_e32 v43, v43
	v_exp_f32_e32 v13, v13
	v_exp_f32_e32 v14, v14
	v_exp_f32_e32 v15, v15
	v_exp_f32_e32 v16, v16
	v_exp_f32_e32 v17, v17
	v_exp_f32_e32 v18, v18
	v_exp_f32_e32 v19, v19
	v_exp_f32_e32 v20, v20
	v_add_f32_e32 v21, 1.0, v21
	v_add_f32_e32 v22, 1.0, v22
	v_add_f32_e32 v23, 1.0, v23
	v_add_f32_e32 v24, 1.0, v24
	v_add_f32_e32 v25, 1.0, v25
	v_add_f32_e32 v26, 1.0, v26
	v_add_f32_e32 v37, 1.0, v37
	v_add_f32_e32 v43, 1.0, v43
	v_add_f32_e32 v13, 1.0, v13
	v_add_f32_e32 v14, 1.0, v14
	v_add_f32_e32 v15, 1.0, v15
	v_add_f32_e32 v16, 1.0, v16
	v_add_f32_e32 v17, 1.0, v17
	v_add_f32_e32 v18, 1.0, v18
	v_add_f32_e32 v19, 1.0, v19
	v_add_f32_e32 v20, 1.0, v20
	v_rcp_f32_e32 v21, v21
	v_rcp_f32_e32 v22, v22
	v_rcp_f32_e32 v23, v23
	v_rcp_f32_e32 v24, v24
	v_rcp_f32_e32 v25, v25
	v_rcp_f32_e32 v26, v26
	v_rcp_f32_e32 v37, v37
	v_rcp_f32_e32 v43, v43
	v_rcp_f32_e32 v13, v13
	v_rcp_f32_e32 v14, v14
	v_rcp_f32_e32 v15, v15
	v_rcp_f32_e32 v16, v16
	v_rcp_f32_e32 v17, v17
	v_rcp_f32_e32 v18, v18
	v_rcp_f32_e32 v19, v19
	v_rcp_f32_e32 v20, v20
	v_mul_f32_e32 v28, v28, v21
	v_mul_f32_e32 v29, v29, v22
	v_mul_f32_e32 v30, v30, v23
	v_mul_f32_e32 v31, v31, v24
	v_mul_f32_e32 v32, v32, v25
	v_mul_f32_e32 v33, v33, v26
	v_mul_f32_e32 v34, v34, v37
	v_mul_f32_e32 v35, v35, v43
	v_mul_f32_e32 v38, v38, v13
	v_mul_f32_e32 v39, v39, v14
	v_mul_f32_e32 v40, v40, v15
	v_mul_f32_e32 v41, v41, v16
	v_mul_f32_e32 v44, v44, v17
	v_mul_f32_e32 v45, v45, v18
	v_mul_f32_e32 v46, v46, v19
	v_mul_f32_e32 v47, v47, v20
	v_mul_f32_e32 v21, 0xbfb8aa3b, v54
	v_mul_f32_e32 v22, 0xbfb8aa3b, v55
	v_mul_f32_e32 v23, 0xbfb8aa3b, v56
	v_mul_f32_e32 v24, 0xbfb8aa3b, v57
	v_mul_f32_e32 v25, 0xbfb8aa3b, v62
	v_mul_f32_e32 v26, 0xbfb8aa3b, v63
	v_mul_f32_e32 v37, 0xbfb8aa3b, v64
	v_mul_f32_e32 v43, 0xbfb8aa3b, v65
	v_mul_f32_e32 v13, 0xbfb8aa3b, v78
	v_mul_f32_e32 v14, 0xbfb8aa3b, v79
	v_mul_f32_e32 v15, 0xbfb8aa3b, v80
	v_mul_f32_e32 v16, 0xbfb8aa3b, v81
	v_mul_f32_e32 v17, 0xbfb8aa3b, v88
	v_mul_f32_e32 v18, 0xbfb8aa3b, v89
	v_mul_f32_e32 v19, 0xbfb8aa3b, v90
	v_mul_f32_e32 v20, 0xbfb8aa3b, v91
	v_exp_f32_e32 v21, v21
	v_exp_f32_e32 v22, v22
	v_exp_f32_e32 v23, v23
	v_exp_f32_e32 v24, v24
	v_exp_f32_e32 v25, v25
	v_exp_f32_e32 v26, v26
	v_exp_f32_e32 v37, v37
	v_exp_f32_e32 v43, v43
	v_exp_f32_e32 v13, v13
	v_exp_f32_e32 v14, v14
	v_exp_f32_e32 v15, v15
	v_exp_f32_e32 v16, v16
	v_exp_f32_e32 v17, v17
	v_exp_f32_e32 v18, v18
	v_exp_f32_e32 v19, v19
	v_exp_f32_e32 v20, v20
	v_add_f32_e32 v21, 1.0, v21
	v_add_f32_e32 v22, 1.0, v22
	v_add_f32_e32 v23, 1.0, v23
	v_add_f32_e32 v24, 1.0, v24
	v_add_f32_e32 v25, 1.0, v25
	v_add_f32_e32 v26, 1.0, v26
	v_add_f32_e32 v37, 1.0, v37
	v_add_f32_e32 v43, 1.0, v43
	v_add_f32_e32 v13, 1.0, v13
	v_add_f32_e32 v14, 1.0, v14
	v_add_f32_e32 v15, 1.0, v15
	v_add_f32_e32 v16, 1.0, v16
	v_add_f32_e32 v17, 1.0, v17
	v_add_f32_e32 v18, 1.0, v18
	v_add_f32_e32 v19, 1.0, v19
	v_add_f32_e32 v20, 1.0, v20
	v_rcp_f32_e32 v21, v21
	v_rcp_f32_e32 v22, v22
	v_rcp_f32_e32 v23, v23
	v_rcp_f32_e32 v24, v24
	v_rcp_f32_e32 v25, v25
	v_rcp_f32_e32 v26, v26
	v_rcp_f32_e32 v37, v37
	v_rcp_f32_e32 v43, v43
	v_rcp_f32_e32 v13, v13
	v_rcp_f32_e32 v14, v14
	v_rcp_f32_e32 v15, v15
	v_rcp_f32_e32 v16, v16
	v_rcp_f32_e32 v17, v17
	v_rcp_f32_e32 v18, v18
	v_rcp_f32_e32 v19, v19
	v_rcp_f32_e32 v20, v20
	v_mul_f32_e32 v54, v54, v21
	v_mul_f32_e32 v55, v55, v22
	v_mul_f32_e32 v56, v56, v23
	v_mul_f32_e32 v57, v57, v24
	v_mul_f32_e32 v62, v62, v25
	v_mul_f32_e32 v63, v63, v26
	v_mul_f32_e32 v64, v64, v37
	v_mul_f32_e32 v65, v65, v43
	v_mul_f32_e32 v78, v78, v13
	v_mul_f32_e32 v79, v79, v14
	v_mul_f32_e32 v80, v80, v15
	v_mul_f32_e32 v81, v81, v16
	v_mul_f32_e32 v88, v88, v17
	v_mul_f32_e32 v89, v89, v18
	v_mul_f32_e32 v90, v90, v19
	v_mul_f32_e32 v91, v91, v20
	v_cvt_pk_bf16_f32 v28, v28, v29
	v_cvt_pk_bf16_f32 v29, v30, v31
	v_cvt_pk_bf16_f32 v32, v32, v33
	v_cvt_pk_bf16_f32 v33, v34, v35
	v_cvt_pk_bf16_f32 v38, v38, v39
	v_cvt_pk_bf16_f32 v39, v40, v41
	v_cvt_pk_bf16_f32 v44, v44, v45
	v_cvt_pk_bf16_f32 v45, v46, v47
	v_cvt_pk_bf16_f32 v54, v54, v55
	v_cvt_pk_bf16_f32 v55, v56, v57
	v_cvt_pk_bf16_f32 v62, v62, v63
	v_cvt_pk_bf16_f32 v63, v64, v65
	v_cvt_pk_bf16_f32 v78, v78, v79
	v_cvt_pk_bf16_f32 v79, v80, v81
	v_cvt_pk_bf16_f32 v88, v88, v89
	v_cvt_pk_bf16_f32 v89, v90, v91
	global_store_dwordx2 v[8:9], v[28:29], off
	v_lshl_add_u64 v[8:9], v[8:9], 0, s[8:9]
	global_store_dwordx2 v[8:9], v[32:33], off
	v_lshl_add_u64 v[8:9], v[8:9], 0, s[8:9]
	global_store_dwordx2 v[8:9], v[38:39], off
	v_lshl_add_u64 v[8:9], v[8:9], 0, s[8:9]
	global_store_dwordx2 v[8:9], v[44:45], off
	v_lshl_add_u64 v[8:9], v[8:9], 0, s[8:9]
	global_store_dwordx2 v[8:9], v[54:55], off
	v_lshl_add_u64 v[8:9], v[8:9], 0, s[8:9]
	global_store_dwordx2 v[8:9], v[62:63], off
	v_lshl_add_u64 v[8:9], v[8:9], 0, s[8:9]
	global_store_dwordx2 v[8:9], v[78:79], off
	v_lshl_add_u64 v[8:9], v[8:9], 0, s[8:9]
	global_store_dwordx2 v[8:9], v[88:89], off
	v_lshl_add_u64 v[8:9], v[8:9], 0, s[8:9]
	s_add_i32 s18, s18, s17
	s_cmp_lt_u32 s18, s16
	s_barrier
	s_cbranch_scc1 .LBB0_988
